# also hoist rowsq loads in the in-proj epilogues (conv/pool/v paths of L1 and order-B tiles), dropping per-group vmcnt(0) waits
# speedup vs baseline: 1.0082x; 1.0009x over previous
; __device__ __forceinline__ float sigm(float v) { return __builtin_amdgcn_rcpf(1.f + __builtin_amdgcn_exp2f(-1.4426950408889634f * v)); }
;     __device__ __forceinline__ void operator()(const f32x4 (&acc)[2][2][4][2], const Unit& u, int wr, int wc, int fr, int fq) const {
;         const int pn = u.pn, pm = u.pm;
;         const bool isctx = pm >= 64;
;         const int v = isctx ? 2 : (pm >> 5);
;         const int cb = pn * 256 + wc * 32 + 8 * fq;
;         f32x4 bv[2][2];
; #pragma unroll
;         for (int bj = 0; bj < 2; ++bj)
; #pragma unroll
;             for (int n = 0; n < 2; ++n) bv[bj][n] = *(const f32x4*)(bias + v * INW + cb + 128 * bj + 4 * n);
;     ...
;         } else {
;             const int ch0 = 128 * (pn - 7) + 32 * wc + 8 * fq;
; #pragma unroll
;             for (int ai = 0; ai < 2; ++ai)
; #pragma unroll
;                 for (int m = 0; m < 4; ++m) {
;                     const int row = pm * 256 + ai * 128 + wr * 64 + m * 16 + fr;
;                     const float rinv = rsqrtf(rowsq[row] * (1.f / DM) + EPSN);
; #pragma unroll
;                     for (int n = 0; n < 2; ++n) {
;                         const f32x4 a = acc[ai][0][m][n] * rinv + bv[0][n], g = acc[ai][1][m][n] * rinv + bv[1][n];
;                         f32x4 o;
; #pragma unroll
;                         for (int j = 0; j < 4; ++j) o[j] = a[j] * sigm(g[j]);
;                         *(f32x4*)(uconv + (size_t)row * 256 + ch0 + 4 * n) = o;
;                     }
;                 }
.LBB0_215:
	s_min_i32 s0, s6, 64
	s_lshr_b32 s0, s0, 5
	s_mulk_i32 s0, 0x900
	s_ashr_i32 s1, s0, 31
	s_lshl_b64 s[0:1], s[0:1], 2
	v_lshl_or_b32 v32, s36, 8, v197
	s_add_u32 s0, s52, s0
	s_addc_u32 s1, s53, s1
	v_ashrrev_i32_e32 v33, 31, v32
	v_lshl_add_u64 v[32:33], v[32:33], 2, s[0:1]
	flat_load_dwordx4 v[44:47], v[32:33]
	flat_load_dwordx4 v[40:43], v[32:33] offset:16
	flat_load_dwordx4 v[36:39], v[32:33] offset:512
	s_nop 0
	flat_load_dwordx4 v[32:35], v[32:33] offset:528
	s_cmp_gt_i32 s6, 63
	s_cselect_b64 s[4:5], -1, 0
	s_cmp_lt_i32 s6, 64
	s_cselect_b64 s[54:55], -1, 0
	s_cmp_gt_i32 s36, 3
	s_mov_b64 s[0:1], -1
	s_cbranch_scc0 .LBB0_226
	s_cmp_gt_u32 s36, 5
	s_cbranch_scc0 .LBB0_222
	s_cmp_lg_u32 s36, 6
	v_lshl_add_u32 v144, s6, 8, v173
	s_cbranch_scc0 .LBB0_219
	v_ashrrev_i32_e32 v145, 31, v144
	v_lshl_add_u64 v[146:147], v[144:145], 2, s[16:17]
	flat_load_dword v148, v[146:147]
	flat_load_dword v214, v[146:147] offset:64
	flat_load_dword v215, v[146:147] offset:128
	flat_load_dword v216, v[146:147] offset:192
	flat_load_dword v217, v[146:147] offset:512
	flat_load_dword v218, v[146:147] offset:576
	flat_load_dword v219, v[146:147] offset:640
	flat_load_dword v220, v[146:147] offset:704
	v_lshl_add_u32 v176, s36, 7, v198
	s_mov_b64 s[0:1], 0
	s_waitcnt vmcnt(0) lgkmcnt(0)
	v_fmamk_f32 v148, v148, 0x3a800000, v224
	v_cmp_gt_f32_e32 vcc, s33, v148
	v_mul_f32_e32 v149, 0x4b800000, v148
	s_nop 0
	v_cndmask_b32_e32 v148, v148, v149, vcc
	v_rsq_f32_e32 v148, v148
	s_nop 0
	v_mul_f32_e32 v149, 0x45800000, v148
	v_cndmask_b32_e32 v150, v148, v149, vcc
	v_lshlrev_b64 v[148:149], 10, v[144:145]
	v_fma_f32 v145, v132, v150, v36
	v_mul_f32_e32 v145, 0xbfb8aa3b, v145
	v_exp_f32_e32 v145, v145
	v_pk_fma_f32 v[158:159], v[140:141], v[150:151], v[44:45] op_sel_hi:[1,0,1]
	v_pk_fma_f32 v[156:157], v[142:143], v[150:151], v[46:47] op_sel_hi:[1,0,1]
	v_add_f32_e32 v145, 1.0, v145
	v_rcp_f32_e32 v152, v145
	v_fma_f32 v145, v133, v150, v37
	v_mul_f32_e32 v145, 0xbfb8aa3b, v145
	v_exp_f32_e32 v145, v145
	s_nop 0
	v_add_f32_e32 v145, 1.0, v145
	v_rcp_f32_e32 v153, v145
	v_fma_f32 v145, v134, v150, v38
	v_mul_f32_e32 v145, 0xbfb8aa3b, v145
	v_exp_f32_e32 v145, v145
	s_nop 0
	v_add_f32_e32 v145, 1.0, v145
	v_rcp_f32_e32 v154, v145
	v_fma_f32 v145, v135, v150, v39
	v_mul_f32_e32 v145, 0xbfb8aa3b, v145
	v_exp_f32_e32 v145, v145
	s_nop 0
	v_add_f32_e32 v145, 1.0, v145
	v_rcp_f32_e32 v155, v145
	v_fma_f32 v145, v128, v150, v32
	v_mul_f32_e32 v145, 0xbfb8aa3b, v145
	v_exp_f32_e32 v145, v145
	v_pk_mul_f32 v[156:157], v[156:157], v[154:155]
	v_pk_mul_f32 v[154:155], v[158:159], v[152:153]
	v_lshl_add_u64 v[152:153], s[20:21], 0, v[148:149]
	v_lshlrev_b64 v[148:149], 2, v[176:177]
	v_lshl_add_u64 v[152:153], v[152:153], 0, v[148:149]
	v_add_f32_e32 v145, 1.0, v145
	flat_store_dwordx4 v[152:153], v[154:157]
	v_pk_fma_f32 v[158:159], v[136:137], v[150:151], v[40:41] op_sel_hi:[1,0,1]
	s_nop 0
	v_rcp_f32_e32 v154, v145
	v_fma_f32 v145, v129, v150, v33
	v_mul_f32_e32 v145, 0xbfb8aa3b, v145
	v_exp_f32_e32 v145, v145
	s_nop 0
	v_add_f32_e32 v145, 1.0, v145
	v_rcp_f32_e32 v155, v145
	v_fma_f32 v145, v130, v150, v34
	v_mul_f32_e32 v145, 0xbfb8aa3b, v145
	v_exp_f32_e32 v145, v145
	v_pk_mul_f32 v[154:155], v[158:159], v[154:155]
	v_add_f32_e32 v145, 1.0, v145
	v_rcp_f32_e32 v156, v145
	v_fma_f32 v145, v131, v150, v35
	v_mul_f32_e32 v145, 0xbfb8aa3b, v145
	v_exp_f32_e32 v145, v145
	v_pk_fma_f32 v[150:151], v[138:139], v[150:151], v[42:43] op_sel_hi:[1,0,1]
	v_add_f32_e32 v145, 1.0, v145
	v_rcp_f32_e32 v157, v145
	s_nop 0
	v_pk_mul_f32 v[156:157], v[150:151], v[156:157]
	flat_store_dwordx4 v[152:153], v[154:157] offset:16
	s_nop 1
	v_or_b32_e32 v150, 16, v144
	v_ashrrev_i32_e32 v151, 31, v150
	v_lshlrev_b64 v[150:151], 10, v[150:151]
	v_lshl_add_u64 v[150:151], s[20:21], 0, v[150:151]
	v_lshl_add_u64 v[150:151], v[150:151], 0, v[148:149]
	v_fmamk_f32 v145, v214, 0x3a800000, v224
	v_cmp_gt_f32_e32 vcc, s33, v145
	v_mul_f32_e32 v152, 0x4b800000, v145
	s_nop 0
	v_cndmask_b32_e32 v145, v145, v152, vcc
	v_rsq_f32_e32 v145, v145
	s_nop 0
	v_mul_f32_e32 v152, 0x45800000, v145
	v_cndmask_b32_e32 v152, v145, v152, vcc
	v_fma_f32 v145, v116, v152, v36
	v_mul_f32_e32 v145, 0xbfb8aa3b, v145
	v_exp_f32_e32 v145, v145
	v_pk_fma_f32 v[158:159], v[124:125], v[152:153], v[44:45] op_sel_hi:[1,0,1]
	v_pk_fma_f32 v[186:187], v[126:127], v[152:153], v[46:47] op_sel_hi:[1,0,1]
	v_add_f32_e32 v145, 1.0, v145
	v_rcp_f32_e32 v154, v145
	v_fma_f32 v145, v117, v152, v37
	v_mul_f32_e32 v145, 0xbfb8aa3b, v145
	v_exp_f32_e32 v145, v145
	s_nop 0
	v_add_f32_e32 v145, 1.0, v145
	v_rcp_f32_e32 v155, v145
	v_fma_f32 v145, v118, v152, v38
	v_mul_f32_e32 v145, 0xbfb8aa3b, v145
	v_exp_f32_e32 v145, v145
	v_pk_mul_f32 v[154:155], v[158:159], v[154:155]
	v_pk_fma_f32 v[158:159], v[120:121], v[152:153], v[40:41] op_sel_hi:[1,0,1]
	v_add_f32_e32 v145, 1.0, v145
	v_rcp_f32_e32 v156, v145
	v_fma_f32 v145, v119, v152, v39
	v_mul_f32_e32 v145, 0xbfb8aa3b, v145
	v_exp_f32_e32 v145, v145
	s_nop 0
	v_add_f32_e32 v145, 1.0, v145
	v_rcp_f32_e32 v157, v145
	v_fma_f32 v145, v112, v152, v32
	v_mul_f32_e32 v145, 0xbfb8aa3b, v145
	v_exp_f32_e32 v145, v145
	v_pk_mul_f32 v[156:157], v[186:187], v[156:157]
	flat_store_dwordx4 v[150:151], v[154:157]
	v_add_f32_e32 v145, 1.0, v145
	s_nop 0
	v_rcp_f32_e32 v156, v145
	v_fma_f32 v145, v113, v152, v33
	v_mul_f32_e32 v145, 0xbfb8aa3b, v145
	v_exp_f32_e32 v145, v145
	s_nop 0
	v_add_f32_e32 v145, 1.0, v145
	v_rcp_f32_e32 v157, v145
	v_fma_f32 v145, v114, v152, v34
	v_mul_f32_e32 v145, 0xbfb8aa3b, v145
	v_exp_f32_e32 v145, v145
	s_nop 0
	v_add_f32_e32 v145, 1.0, v145
	v_rcp_f32_e32 v154, v145
; __device__ __forceinline__ float sigm(float v) { return __builtin_amdgcn_rcpf(1.f + __builtin_amdgcn_exp2f(-1.4426950408889634f * v)); }
;     __device__ __forceinline__ void operator()(const f32x4 (&acc)[2][2][4][2], const Unit& u, int wr, int wc, int fr, int fq) const {
;     ...
;             const int ch0 = 128 * (pn - 7) + 32 * wc + 8 * fq;
; #pragma unroll
;             for (int ai = 0; ai < 2; ++ai)
; #pragma unroll
;                 for (int m = 0; m < 4; ++m) {
;                     const int row = pm * 256 + ai * 128 + wr * 64 + m * 16 + fr;
;                     const float rinv = rsqrtf(rowsq[row] * (1.f / DM) + EPSN);
; #pragma unroll
;                     for (int n = 0; n < 2; ++n) {
;                         const f32x4 a = acc[ai][0][m][n] * rinv + bv[0][n], g = acc[ai][1][m][n] * rinv + bv[1][n];
;                         f32x4 o;
; #pragma unroll
;                         for (int j = 0; j < 4; ++j) o[j] = a[j] * sigm(g[j]);
;                         *(f32x4*)(uconv + (size_t)row * 256 + ch0 + 4 * n) = o;
;                     }
	v_fma_f32 v145, v115, v152, v35
	v_mul_f32_e32 v145, 0xbfb8aa3b, v145
	v_exp_f32_e32 v145, v145
	v_pk_fma_f32 v[152:153], v[122:123], v[152:153], v[42:43] op_sel_hi:[1,0,1]
	v_add_f32_e32 v145, 1.0, v145
	v_rcp_f32_e32 v155, v145
	s_nop 0
	v_pk_mul_f32 v[154:155], v[152:153], v[154:155]
	v_pk_mul_f32 v[152:153], v[158:159], v[156:157]
	flat_store_dwordx4 v[150:151], v[152:155] offset:16
	s_nop 1
	v_or_b32_e32 v150, 32, v144
	v_ashrrev_i32_e32 v151, 31, v150
	v_lshlrev_b64 v[150:151], 10, v[150:151]
	v_lshl_add_u64 v[150:151], s[20:21], 0, v[150:151]
	v_lshl_add_u64 v[150:151], v[150:151], 0, v[148:149]
	v_fmamk_f32 v145, v215, 0x3a800000, v224
	v_cmp_gt_f32_e32 vcc, s33, v145
	v_mul_f32_e32 v152, 0x4b800000, v145
	s_nop 0
	v_cndmask_b32_e32 v145, v145, v152, vcc
	v_rsq_f32_e32 v145, v145
	s_nop 0
	v_mul_f32_e32 v152, 0x45800000, v145
	v_cndmask_b32_e32 v152, v145, v152, vcc
	v_fma_f32 v145, v100, v152, v36
	v_mul_f32_e32 v145, 0xbfb8aa3b, v145
	v_exp_f32_e32 v145, v145
	v_pk_fma_f32 v[158:159], v[108:109], v[152:153], v[44:45] op_sel_hi:[1,0,1]
	v_pk_fma_f32 v[186:187], v[110:111], v[152:153], v[46:47] op_sel_hi:[1,0,1]
	v_add_f32_e32 v145, 1.0, v145
	v_rcp_f32_e32 v154, v145
	v_fma_f32 v145, v101, v152, v37
	v_mul_f32_e32 v145, 0xbfb8aa3b, v145
	v_exp_f32_e32 v145, v145
	s_nop 0
	v_add_f32_e32 v145, 1.0, v145
	v_rcp_f32_e32 v155, v145
	v_fma_f32 v145, v102, v152, v38
	v_mul_f32_e32 v145, 0xbfb8aa3b, v145
	v_exp_f32_e32 v145, v145
	v_pk_mul_f32 v[154:155], v[158:159], v[154:155]
	v_pk_fma_f32 v[158:159], v[104:105], v[152:153], v[40:41] op_sel_hi:[1,0,1]
	v_add_f32_e32 v145, 1.0, v145
	v_rcp_f32_e32 v156, v145
	v_fma_f32 v145, v103, v152, v39
	v_mul_f32_e32 v145, 0xbfb8aa3b, v145
	v_exp_f32_e32 v145, v145
	s_nop 0
	v_add_f32_e32 v145, 1.0, v145
	v_rcp_f32_e32 v157, v145
	v_fma_f32 v145, v96, v152, v32
	v_mul_f32_e32 v145, 0xbfb8aa3b, v145
	v_exp_f32_e32 v145, v145
	v_pk_mul_f32 v[156:157], v[186:187], v[156:157]
	flat_store_dwordx4 v[150:151], v[154:157]
	v_add_f32_e32 v145, 1.0, v145
	s_nop 0
	v_rcp_f32_e32 v156, v145
	v_fma_f32 v145, v97, v152, v33
	v_mul_f32_e32 v145, 0xbfb8aa3b, v145
	v_exp_f32_e32 v145, v145
	s_nop 0
	v_add_f32_e32 v145, 1.0, v145
	v_rcp_f32_e32 v157, v145
	v_fma_f32 v145, v98, v152, v34
	v_mul_f32_e32 v145, 0xbfb8aa3b, v145
	v_exp_f32_e32 v145, v145
	s_nop 0
	v_add_f32_e32 v145, 1.0, v145
	v_rcp_f32_e32 v154, v145
	v_fma_f32 v145, v99, v152, v35
	v_mul_f32_e32 v145, 0xbfb8aa3b, v145
	v_exp_f32_e32 v145, v145
	v_pk_fma_f32 v[152:153], v[106:107], v[152:153], v[42:43] op_sel_hi:[1,0,1]
	v_add_f32_e32 v145, 1.0, v145
	v_rcp_f32_e32 v155, v145
	s_nop 0
	v_pk_mul_f32 v[154:155], v[152:153], v[154:155]
	v_pk_mul_f32 v[152:153], v[158:159], v[156:157]
	flat_store_dwordx4 v[150:151], v[152:155] offset:16
	s_nop 1
	v_or_b32_e32 v150, 48, v144
	v_ashrrev_i32_e32 v151, 31, v150
	v_lshlrev_b64 v[150:151], 10, v[150:151]
	v_lshl_add_u64 v[150:151], s[20:21], 0, v[150:151]
	v_lshl_add_u64 v[150:151], v[150:151], 0, v[148:149]
	v_fmamk_f32 v145, v216, 0x3a800000, v224
	v_cmp_gt_f32_e32 vcc, s33, v145
	v_mul_f32_e32 v152, 0x4b800000, v145
	s_nop 0
	v_cndmask_b32_e32 v145, v145, v152, vcc
	v_rsq_f32_e32 v145, v145
	s_nop 0
	v_mul_f32_e32 v152, 0x45800000, v145
	v_cndmask_b32_e32 v152, v145, v152, vcc
	v_fma_f32 v145, v84, v152, v36
	v_mul_f32_e32 v145, 0xbfb8aa3b, v145
	v_exp_f32_e32 v145, v145
	v_pk_fma_f32 v[158:159], v[92:93], v[152:153], v[44:45] op_sel_hi:[1,0,1]
	v_pk_fma_f32 v[186:187], v[94:95], v[152:153], v[46:47] op_sel_hi:[1,0,1]
	v_add_f32_e32 v145, 1.0, v145
	v_rcp_f32_e32 v154, v145
	v_fma_f32 v145, v85, v152, v37
	v_mul_f32_e32 v145, 0xbfb8aa3b, v145
	v_exp_f32_e32 v145, v145
	s_nop 0
	v_add_f32_e32 v145, 1.0, v145
	v_rcp_f32_e32 v155, v145
	v_fma_f32 v145, v86, v152, v38
	v_mul_f32_e32 v145, 0xbfb8aa3b, v145
	v_exp_f32_e32 v145, v145
	v_pk_mul_f32 v[154:155], v[158:159], v[154:155]
	v_pk_fma_f32 v[158:159], v[88:89], v[152:153], v[40:41] op_sel_hi:[1,0,1]
	v_add_f32_e32 v145, 1.0, v145
	v_rcp_f32_e32 v156, v145
	v_fma_f32 v145, v87, v152, v39
	v_mul_f32_e32 v145, 0xbfb8aa3b, v145
	v_exp_f32_e32 v145, v145
	s_nop 0
	v_add_f32_e32 v145, 1.0, v145
	v_rcp_f32_e32 v157, v145
	v_fma_f32 v145, v80, v152, v32
	v_mul_f32_e32 v145, 0xbfb8aa3b, v145
	v_exp_f32_e32 v145, v145
	v_pk_mul_f32 v[156:157], v[186:187], v[156:157]
	flat_store_dwordx4 v[150:151], v[154:157]
	v_add_f32_e32 v145, 1.0, v145
	s_nop 0
	v_rcp_f32_e32 v156, v145
	v_fma_f32 v145, v81, v152, v33
	v_mul_f32_e32 v145, 0xbfb8aa3b, v145
	v_exp_f32_e32 v145, v145
	s_nop 0
	v_add_f32_e32 v145, 1.0, v145
	v_rcp_f32_e32 v157, v145
	v_fma_f32 v145, v82, v152, v34
	v_mul_f32_e32 v145, 0xbfb8aa3b, v145
	v_exp_f32_e32 v145, v145
	s_nop 0
	v_add_f32_e32 v145, 1.0, v145
	v_rcp_f32_e32 v154, v145
	v_fma_f32 v145, v83, v152, v35
	v_mul_f32_e32 v145, 0xbfb8aa3b, v145
	v_exp_f32_e32 v145, v145
	v_pk_fma_f32 v[152:153], v[90:91], v[152:153], v[42:43] op_sel_hi:[1,0,1]
	v_add_f32_e32 v145, 1.0, v145
	v_rcp_f32_e32 v155, v145
	s_nop 0
	v_pk_mul_f32 v[154:155], v[152:153], v[154:155]
	v_pk_mul_f32 v[152:153], v[158:159], v[156:157]
	flat_store_dwordx4 v[150:151], v[152:155] offset:16
	s_nop 1
	v_add_u32_e32 v150, 0x80, v144
	v_ashrrev_i32_e32 v151, 31, v150
	v_lshlrev_b64 v[150:151], 10, v[150:151]
	v_lshl_add_u64 v[150:151], s[20:21], 0, v[150:151]
	v_lshl_add_u64 v[150:151], v[150:151], 0, v[148:149]
	v_fmamk_f32 v145, v217, 0x3a800000, v224
	v_cmp_gt_f32_e32 vcc, s33, v145
	v_mul_f32_e32 v152, 0x4b800000, v145
	s_nop 0
	v_cndmask_b32_e32 v145, v145, v152, vcc
	v_rsq_f32_e32 v145, v145
	s_nop 0
	v_mul_f32_e32 v152, 0x45800000, v145
	v_cndmask_b32_e32 v152, v145, v152, vcc
; __device__ __forceinline__ float sigm(float v) { return __builtin_amdgcn_rcpf(1.f + __builtin_amdgcn_exp2f(-1.4426950408889634f * v)); }
;     __device__ __forceinline__ void operator()(const f32x4 (&acc)[2][2][4][2], const Unit& u, int wr, int wc, int fr, int fq) const {
;     ...
;             const int ch0 = 128 * (pn - 7) + 32 * wc + 8 * fq;
; #pragma unroll
;             for (int ai = 0; ai < 2; ++ai)
; #pragma unroll
;                 for (int m = 0; m < 4; ++m) {
;                     const int row = pm * 256 + ai * 128 + wr * 64 + m * 16 + fr;
;                     const float rinv = rsqrtf(rowsq[row] * (1.f / DM) + EPSN);
; #pragma unroll
;                     for (int n = 0; n < 2; ++n) {
;                         const f32x4 a = acc[ai][0][m][n] * rinv + bv[0][n], g = acc[ai][1][m][n] * rinv + bv[1][n];
;                         f32x4 o;
; #pragma unroll
;                         for (int j = 0; j < 4; ++j) o[j] = a[j] * sigm(g[j]);
;                         *(f32x4*)(uconv + (size_t)row * 256 + ch0 + 4 * n) = o;
;                     }
	v_fma_f32 v145, v68, v152, v36
	v_mul_f32_e32 v145, 0xbfb8aa3b, v145
	v_exp_f32_e32 v145, v145
	v_pk_fma_f32 v[158:159], v[76:77], v[152:153], v[44:45] op_sel_hi:[1,0,1]
	v_pk_fma_f32 v[186:187], v[78:79], v[152:153], v[46:47] op_sel_hi:[1,0,1]
	v_add_f32_e32 v145, 1.0, v145
	v_rcp_f32_e32 v154, v145
	v_fma_f32 v145, v69, v152, v37
	v_mul_f32_e32 v145, 0xbfb8aa3b, v145
	v_exp_f32_e32 v145, v145
	s_nop 0
	v_add_f32_e32 v145, 1.0, v145
	v_rcp_f32_e32 v155, v145
	v_fma_f32 v145, v70, v152, v38
	v_mul_f32_e32 v145, 0xbfb8aa3b, v145
	v_exp_f32_e32 v145, v145
	v_pk_mul_f32 v[154:155], v[158:159], v[154:155]
	v_pk_fma_f32 v[158:159], v[72:73], v[152:153], v[40:41] op_sel_hi:[1,0,1]
	v_add_f32_e32 v145, 1.0, v145
	v_rcp_f32_e32 v156, v145
	v_fma_f32 v145, v71, v152, v39
	v_mul_f32_e32 v145, 0xbfb8aa3b, v145
	v_exp_f32_e32 v145, v145
	s_nop 0
	v_add_f32_e32 v145, 1.0, v145
	v_rcp_f32_e32 v157, v145
	v_fma_f32 v145, v64, v152, v32
	v_mul_f32_e32 v145, 0xbfb8aa3b, v145
	v_exp_f32_e32 v145, v145
	v_pk_mul_f32 v[156:157], v[186:187], v[156:157]
	flat_store_dwordx4 v[150:151], v[154:157]
	v_add_f32_e32 v145, 1.0, v145
	s_nop 0
	v_rcp_f32_e32 v156, v145
	v_fma_f32 v145, v65, v152, v33
	v_mul_f32_e32 v145, 0xbfb8aa3b, v145
	v_exp_f32_e32 v145, v145
	s_nop 0
	v_add_f32_e32 v145, 1.0, v145
	v_rcp_f32_e32 v157, v145
	v_fma_f32 v145, v66, v152, v34
	v_mul_f32_e32 v145, 0xbfb8aa3b, v145
	v_exp_f32_e32 v145, v145
	s_nop 0
	v_add_f32_e32 v145, 1.0, v145
	v_rcp_f32_e32 v154, v145
	v_fma_f32 v145, v67, v152, v35
	v_mul_f32_e32 v145, 0xbfb8aa3b, v145
	v_exp_f32_e32 v145, v145
	v_pk_fma_f32 v[152:153], v[74:75], v[152:153], v[42:43] op_sel_hi:[1,0,1]
	v_add_f32_e32 v145, 1.0, v145
	v_rcp_f32_e32 v155, v145
	s_nop 0
	v_pk_mul_f32 v[154:155], v[152:153], v[154:155]
	v_pk_mul_f32 v[152:153], v[158:159], v[156:157]
	flat_store_dwordx4 v[150:151], v[152:155] offset:16
	s_nop 1
	v_add_u32_e32 v150, 0x90, v144
	v_ashrrev_i32_e32 v151, 31, v150
	v_lshlrev_b64 v[150:151], 10, v[150:151]
	v_lshl_add_u64 v[150:151], s[20:21], 0, v[150:151]
	v_lshl_add_u64 v[150:151], v[150:151], 0, v[148:149]
	v_fmamk_f32 v145, v218, 0x3a800000, v224
	v_cmp_gt_f32_e32 vcc, s33, v145
	v_mul_f32_e32 v152, 0x4b800000, v145
	s_nop 0
	v_cndmask_b32_e32 v145, v145, v152, vcc
	v_rsq_f32_e32 v145, v145
	s_nop 0
	v_mul_f32_e32 v152, 0x45800000, v145
	v_cndmask_b32_e32 v152, v145, v152, vcc
	v_fma_f32 v145, v52, v152, v36
	v_mul_f32_e32 v145, 0xbfb8aa3b, v145
	v_exp_f32_e32 v145, v145
	v_pk_fma_f32 v[158:159], v[60:61], v[152:153], v[44:45] op_sel_hi:[1,0,1]
	v_pk_fma_f32 v[186:187], v[62:63], v[152:153], v[46:47] op_sel_hi:[1,0,1]
	v_add_f32_e32 v145, 1.0, v145
	v_rcp_f32_e32 v154, v145
	v_fma_f32 v145, v53, v152, v37
	v_mul_f32_e32 v145, 0xbfb8aa3b, v145
	v_exp_f32_e32 v145, v145
	s_nop 0
	v_add_f32_e32 v145, 1.0, v145
	v_rcp_f32_e32 v155, v145
	v_fma_f32 v145, v54, v152, v38
	v_mul_f32_e32 v145, 0xbfb8aa3b, v145
	v_exp_f32_e32 v145, v145
	v_pk_mul_f32 v[154:155], v[158:159], v[154:155]
	v_pk_fma_f32 v[158:159], v[56:57], v[152:153], v[40:41] op_sel_hi:[1,0,1]
	v_add_f32_e32 v145, 1.0, v145
	v_rcp_f32_e32 v156, v145
	v_fma_f32 v145, v55, v152, v39
	v_mul_f32_e32 v145, 0xbfb8aa3b, v145
	v_exp_f32_e32 v145, v145
	s_nop 0
	v_add_f32_e32 v145, 1.0, v145
	v_rcp_f32_e32 v157, v145
	v_fma_f32 v145, v48, v152, v32
	v_mul_f32_e32 v145, 0xbfb8aa3b, v145
	v_exp_f32_e32 v145, v145
	v_pk_mul_f32 v[156:157], v[186:187], v[156:157]
	flat_store_dwordx4 v[150:151], v[154:157]
	v_add_f32_e32 v145, 1.0, v145
	s_nop 0
	v_rcp_f32_e32 v156, v145
	v_fma_f32 v145, v49, v152, v33
	v_mul_f32_e32 v145, 0xbfb8aa3b, v145
	v_exp_f32_e32 v145, v145
	s_nop 0
	v_add_f32_e32 v145, 1.0, v145
	v_rcp_f32_e32 v157, v145
	v_fma_f32 v145, v50, v152, v34
	v_mul_f32_e32 v145, 0xbfb8aa3b, v145
	v_exp_f32_e32 v145, v145
	s_nop 0
	v_add_f32_e32 v145, 1.0, v145
	v_rcp_f32_e32 v154, v145
	v_fma_f32 v145, v51, v152, v35
	v_mul_f32_e32 v145, 0xbfb8aa3b, v145
	v_exp_f32_e32 v145, v145
	v_pk_fma_f32 v[152:153], v[58:59], v[152:153], v[42:43] op_sel_hi:[1,0,1]
	v_add_f32_e32 v145, 1.0, v145
	v_rcp_f32_e32 v155, v145
	s_nop 0
	v_pk_mul_f32 v[154:155], v[152:153], v[154:155]
	v_pk_mul_f32 v[152:153], v[158:159], v[156:157]
	flat_store_dwordx4 v[150:151], v[152:155] offset:16
	s_nop 1
	v_add_u32_e32 v150, 0xa0, v144
	v_ashrrev_i32_e32 v151, 31, v150
	v_lshlrev_b64 v[150:151], 10, v[150:151]
	v_lshl_add_u64 v[150:151], s[20:21], 0, v[150:151]
	v_lshl_add_u64 v[150:151], v[150:151], 0, v[148:149]
	v_fmamk_f32 v145, v219, 0x3a800000, v224
	v_cmp_gt_f32_e32 vcc, s33, v145
	v_mul_f32_e32 v152, 0x4b800000, v145
	s_nop 0
	v_cndmask_b32_e32 v145, v145, v152, vcc
	v_rsq_f32_e32 v145, v145
	s_nop 0
	v_mul_f32_e32 v152, 0x45800000, v145
	v_cndmask_b32_e32 v152, v145, v152, vcc
	v_fma_f32 v145, v20, v152, v36
	v_mul_f32_e32 v145, 0xbfb8aa3b, v145
	v_exp_f32_e32 v145, v145
	v_pk_fma_f32 v[158:159], v[28:29], v[152:153], v[44:45] op_sel_hi:[1,0,1]
	v_pk_fma_f32 v[186:187], v[30:31], v[152:153], v[46:47] op_sel_hi:[1,0,1]
	v_add_f32_e32 v145, 1.0, v145
	v_rcp_f32_e32 v154, v145
	v_fma_f32 v145, v21, v152, v37
	v_mul_f32_e32 v145, 0xbfb8aa3b, v145
	v_exp_f32_e32 v145, v145
	s_nop 0
	v_add_f32_e32 v145, 1.0, v145
	v_rcp_f32_e32 v155, v145
	v_fma_f32 v145, v22, v152, v38
	v_mul_f32_e32 v145, 0xbfb8aa3b, v145
	v_exp_f32_e32 v145, v145
	v_pk_mul_f32 v[154:155], v[158:159], v[154:155]
	v_pk_fma_f32 v[158:159], v[24:25], v[152:153], v[40:41] op_sel_hi:[1,0,1]
	v_add_f32_e32 v145, 1.0, v145
	v_rcp_f32_e32 v156, v145
	v_fma_f32 v145, v23, v152, v39
	v_mul_f32_e32 v145, 0xbfb8aa3b, v145
	v_exp_f32_e32 v145, v145
	s_nop 0
	v_add_f32_e32 v145, 1.0, v145
	v_rcp_f32_e32 v157, v145
; __device__ __forceinline__ float sigm(float v) { return __builtin_amdgcn_rcpf(1.f + __builtin_amdgcn_exp2f(-1.4426950408889634f * v)); }
;     __device__ __forceinline__ void operator()(const f32x4 (&acc)[2][2][4][2], const Unit& u, int wr, int wc, int fr, int fq) const {
;     ...
;         } else if (pn == 6) {
; #pragma unroll
;             for (int ai = 0; ai < 2; ++ai)
; #pragma unroll
;                 for (int m = 0; m < 4; ++m) {
;                     const int row = pm * 256 + ai * 128 + wr * 64 + m * 16 + fr;
;                     const float rinv = rsqrtf(rowsq[row] * (1.f / DM) + EPSN);
; #pragma unroll
;                     for (int bj = 0; bj < 2; ++bj)
; #pragma unroll
;                         for (int n = 0; n < 2; ++n) *(f32x4*)(upool + (size_t)row * 256 + 128 * bj + 32 * wc + 8 * fq + 4 * n) = acc[ai][bj][m][n] * rinv + bv[bj][n];
;                 }
;     ...
;             const int ch0 = 128 * (pn - 7) + 32 * wc + 8 * fq;
; #pragma unroll
;             for (int ai = 0; ai < 2; ++ai)
; #pragma unroll
;                 for (int m = 0; m < 4; ++m) {
;                     const int row = pm * 256 + ai * 128 + wr * 64 + m * 16 + fr;
;                     const float rinv = rsqrtf(rowsq[row] * (1.f / DM) + EPSN);
; #pragma unroll
;                     for (int n = 0; n < 2; ++n) {
;                         const f32x4 a = acc[ai][0][m][n] * rinv + bv[0][n], g = acc[ai][1][m][n] * rinv + bv[1][n];
;                         f32x4 o;
; #pragma unroll
;                         for (int j = 0; j < 4; ++j) o[j] = a[j] * sigm(g[j]);
;                         *(f32x4*)(uconv + (size_t)row * 256 + ch0 + 4 * n) = o;
;                     }
	v_fma_f32 v145, v16, v152, v32
	v_mul_f32_e32 v145, 0xbfb8aa3b, v145
	v_exp_f32_e32 v145, v145
	v_pk_mul_f32 v[156:157], v[186:187], v[156:157]
	flat_store_dwordx4 v[150:151], v[154:157]
	v_add_f32_e32 v145, 1.0, v145
	s_nop 0
	v_rcp_f32_e32 v156, v145
	v_fma_f32 v145, v17, v152, v33
	v_mul_f32_e32 v145, 0xbfb8aa3b, v145
	v_exp_f32_e32 v145, v145
	s_nop 0
	v_add_f32_e32 v145, 1.0, v145
	v_rcp_f32_e32 v157, v145
	v_fma_f32 v145, v18, v152, v34
	v_mul_f32_e32 v145, 0xbfb8aa3b, v145
	v_exp_f32_e32 v145, v145
	s_nop 0
	v_add_f32_e32 v145, 1.0, v145
	v_rcp_f32_e32 v154, v145
	v_fma_f32 v145, v19, v152, v35
	v_mul_f32_e32 v145, 0xbfb8aa3b, v145
	v_exp_f32_e32 v145, v145
	v_pk_fma_f32 v[152:153], v[26:27], v[152:153], v[42:43] op_sel_hi:[1,0,1]
	v_add_f32_e32 v145, 1.0, v145
	v_rcp_f32_e32 v155, v145
	s_nop 0
	v_pk_mul_f32 v[154:155], v[152:153], v[154:155]
	v_pk_mul_f32 v[152:153], v[158:159], v[156:157]
	flat_store_dwordx4 v[150:151], v[152:155] offset:16
	s_nop 1
	v_fmamk_f32 v145, v220, 0x3a800000, v224
	v_cmp_gt_f32_e32 vcc, s33, v145
	v_mul_f32_e32 v146, 0x4b800000, v145
	v_add_u32_e32 v152, 0xb0, v144
	v_cndmask_b32_e32 v145, v145, v146, vcc
	v_rsq_f32_e32 v145, v145
	v_ashrrev_i32_e32 v153, 31, v152
	v_mul_f32_e32 v146, 0x45800000, v145
	v_cndmask_b32_e32 v150, v145, v146, vcc
	v_fma_f32 v145, v4, v150, v36
	v_mul_f32_e32 v145, 0xbfb8aa3b, v145
	v_exp_f32_e32 v145, v145
	v_lshlrev_b64 v[146:147], 10, v[152:153]
	v_lshl_add_u64 v[146:147], s[20:21], 0, v[146:147]
	v_lshl_add_u64 v[146:147], v[146:147], 0, v[148:149]
	v_add_f32_e32 v145, 1.0, v145
	v_rcp_f32_e32 v152, v145
	v_fma_f32 v145, v5, v150, v37
	v_mul_f32_e32 v145, 0xbfb8aa3b, v145
	v_exp_f32_e32 v145, v145
	v_pk_fma_f32 v[156:157], v[12:13], v[150:151], v[44:45] op_sel_hi:[1,0,1]
	v_pk_fma_f32 v[158:159], v[14:15], v[150:151], v[46:47] op_sel_hi:[1,0,1]
	v_add_f32_e32 v145, 1.0, v145
	v_rcp_f32_e32 v153, v145
	v_fma_f32 v145, v6, v150, v38
	v_mul_f32_e32 v145, 0xbfb8aa3b, v145
	v_exp_f32_e32 v145, v145
	v_pk_mul_f32 v[152:153], v[156:157], v[152:153]
	v_add_f32_e32 v145, 1.0, v145
	v_rcp_f32_e32 v154, v145
	v_fma_f32 v145, v7, v150, v39
	v_mul_f32_e32 v145, 0xbfb8aa3b, v145
	v_exp_f32_e32 v145, v145
	s_nop 0
	v_add_f32_e32 v145, 1.0, v145
	v_rcp_f32_e32 v155, v145
	v_fma_f32 v145, v0, v150, v32
	v_mul_f32_e32 v145, 0xbfb8aa3b, v145
	v_exp_f32_e32 v145, v145
	v_pk_mul_f32 v[154:155], v[158:159], v[154:155]
	flat_store_dwordx4 v[146:147], v[152:155]
	v_add_f32_e32 v145, 1.0, v145
	v_rcp_f32_e32 v148, v145
	v_fma_f32 v145, v1, v150, v33
	v_mul_f32_e32 v145, 0xbfb8aa3b, v145
	v_exp_f32_e32 v145, v145
	v_pk_fma_f32 v[154:155], v[8:9], v[150:151], v[40:41] op_sel_hi:[1,0,1]
	v_add_f32_e32 v145, 1.0, v145
	v_rcp_f32_e32 v149, v145
	v_fma_f32 v145, v2, v150, v34
	v_mul_f32_e32 v145, 0xbfb8aa3b, v145
	v_exp_f32_e32 v145, v145
	v_pk_mul_f32 v[148:149], v[154:155], v[148:149]
	v_add_f32_e32 v145, 1.0, v145
	v_rcp_f32_e32 v152, v145
	v_fma_f32 v145, v3, v150, v35
	v_mul_f32_e32 v145, 0xbfb8aa3b, v145
	v_exp_f32_e32 v145, v145
	v_pk_fma_f32 v[150:151], v[10:11], v[150:151], v[42:43] op_sel_hi:[1,0,1]
	v_add_f32_e32 v145, 1.0, v145
	v_rcp_f32_e32 v153, v145
	s_nop 0
	v_pk_mul_f32 v[150:151], v[150:151], v[152:153]
	flat_store_dwordx4 v[146:147], v[148:151] offset:16
.LBB0_219:
	s_andn2_b64 vcc, exec, s[0:1]
	s_cbranch_vccnz .LBB0_221
	v_ashrrev_i32_e32 v145, 31, v144
	v_lshl_add_u64 v[146:147], v[144:145], 2, s[16:17]
	flat_load_dword v148, v[146:147]
	flat_load_dword v214, v[146:147] offset:64
	flat_load_dword v215, v[146:147] offset:128
	flat_load_dword v216, v[146:147] offset:192
	flat_load_dword v217, v[146:147] offset:512
	flat_load_dword v218, v[146:147] offset:576
	flat_load_dword v219, v[146:147] offset:640
	v_lshlrev_b64 v[154:155], 10, v[144:145]
	v_lshl_add_u64 v[154:155], v[174:175], 0, v[154:155]
	s_waitcnt vmcnt(0) lgkmcnt(0)
	v_fmamk_f32 v148, v148, 0x3a800000, v224
	v_cmp_gt_f32_e32 vcc, s33, v148
	v_mul_f32_e32 v149, 0x4b800000, v148
	s_nop 0
	v_cndmask_b32_e32 v148, v148, v149, vcc
	v_rsq_f32_e32 v148, v148
	s_nop 0
	v_mul_f32_e32 v149, 0x45800000, v148
	v_cndmask_b32_e32 v152, v148, v149, vcc
	v_pk_fma_f32 v[150:151], v[142:143], v[152:153], v[46:47] op_sel_hi:[1,0,1]
	v_pk_fma_f32 v[148:149], v[140:141], v[152:153], v[44:45] op_sel_hi:[1,0,1]
	flat_store_dwordx4 v[154:155], v[148:151]
	s_nop 1
	v_pk_fma_f32 v[150:151], v[138:139], v[152:153], v[42:43] op_sel_hi:[1,0,1]
	v_pk_fma_f32 v[148:149], v[136:137], v[152:153], v[40:41] op_sel_hi:[1,0,1]
	flat_store_dwordx4 v[154:155], v[148:151] offset:16
	s_nop 1
	v_pk_fma_f32 v[150:151], v[134:135], v[152:153], v[38:39] op_sel_hi:[1,0,1]
	v_pk_fma_f32 v[148:149], v[132:133], v[152:153], v[36:37] op_sel_hi:[1,0,1]
	flat_store_dwordx4 v[154:155], v[148:151] offset:512
	s_nop 1
	v_pk_fma_f32 v[150:151], v[130:131], v[152:153], v[34:35] op_sel_hi:[1,0,1]
	v_pk_fma_f32 v[148:149], v[128:129], v[152:153], v[32:33] op_sel_hi:[1,0,1]
	flat_store_dwordx4 v[154:155], v[148:151] offset:528
	s_nop 1
	v_fmamk_f32 v145, v214, 0x3a800000, v224
	v_cmp_gt_f32_e32 vcc, s33, v145
	v_mul_f32_e32 v150, 0x4b800000, v145
	v_or_b32_e32 v148, 16, v144
	v_cndmask_b32_e32 v145, v145, v150, vcc
	v_rsq_f32_e32 v145, v145
	v_ashrrev_i32_e32 v149, 31, v148
	v_lshlrev_b64 v[154:155], 10, v[148:149]
	v_lshl_add_u64 v[154:155], v[174:175], 0, v[154:155]
	v_mul_f32_e32 v150, 0x45800000, v145
	v_cndmask_b32_e32 v152, v145, v150, vcc
	v_pk_fma_f32 v[150:151], v[126:127], v[152:153], v[46:47] op_sel_hi:[1,0,1]
	v_pk_fma_f32 v[148:149], v[124:125], v[152:153], v[44:45] op_sel_hi:[1,0,1]
	flat_store_dwordx4 v[154:155], v[148:151]
	s_nop 1
;     __device__ __forceinline__ void operator()(const f32x4 (&acc)[2][2][4][2], const Unit& u, int wr, int wc, int fr, int fq) const {
;     ...
;         } else if (pn == 6) {
; #pragma unroll
;             for (int ai = 0; ai < 2; ++ai)
; #pragma unroll
;                 for (int m = 0; m < 4; ++m) {
;                     const int row = pm * 256 + ai * 128 + wr * 64 + m * 16 + fr;
;                     const float rinv = rsqrtf(rowsq[row] * (1.f / DM) + EPSN);
; #pragma unroll
;                     for (int bj = 0; bj < 2; ++bj)
; #pragma unroll
;                         for (int n = 0; n < 2; ++n) *(f32x4*)(upool + (size_t)row * 256 + 128 * bj + 32 * wc + 8 * fq + 4 * n) = acc[ai][bj][m][n] * rinv + bv[bj][n];
;                 }
	v_pk_fma_f32 v[150:151], v[122:123], v[152:153], v[42:43] op_sel_hi:[1,0,1]
	v_pk_fma_f32 v[148:149], v[120:121], v[152:153], v[40:41] op_sel_hi:[1,0,1]
	flat_store_dwordx4 v[154:155], v[148:151] offset:16
	s_nop 1
	v_pk_fma_f32 v[150:151], v[118:119], v[152:153], v[38:39] op_sel_hi:[1,0,1]
	v_pk_fma_f32 v[148:149], v[116:117], v[152:153], v[36:37] op_sel_hi:[1,0,1]
	flat_store_dwordx4 v[154:155], v[148:151] offset:512
	s_nop 1
	v_pk_fma_f32 v[150:151], v[114:115], v[152:153], v[34:35] op_sel_hi:[1,0,1]
	v_pk_fma_f32 v[148:149], v[112:113], v[152:153], v[32:33] op_sel_hi:[1,0,1]
	flat_store_dwordx4 v[154:155], v[148:151] offset:528
	s_nop 1
	v_fmamk_f32 v145, v215, 0x3a800000, v224
	v_cmp_gt_f32_e32 vcc, s33, v145
	v_mul_f32_e32 v150, 0x4b800000, v145
	v_or_b32_e32 v148, 32, v144
	v_cndmask_b32_e32 v145, v145, v150, vcc
	v_rsq_f32_e32 v145, v145
	v_ashrrev_i32_e32 v149, 31, v148
	v_lshlrev_b64 v[154:155], 10, v[148:149]
	v_lshl_add_u64 v[154:155], v[174:175], 0, v[154:155]
	v_mul_f32_e32 v150, 0x45800000, v145
	v_cndmask_b32_e32 v152, v145, v150, vcc
	v_pk_fma_f32 v[150:151], v[110:111], v[152:153], v[46:47] op_sel_hi:[1,0,1]
	v_pk_fma_f32 v[148:149], v[108:109], v[152:153], v[44:45] op_sel_hi:[1,0,1]
	flat_store_dwordx4 v[154:155], v[148:151]
	s_nop 1
	v_pk_fma_f32 v[150:151], v[106:107], v[152:153], v[42:43] op_sel_hi:[1,0,1]
	v_pk_fma_f32 v[148:149], v[104:105], v[152:153], v[40:41] op_sel_hi:[1,0,1]
	flat_store_dwordx4 v[154:155], v[148:151] offset:16
	s_nop 1
	v_pk_fma_f32 v[150:151], v[102:103], v[152:153], v[38:39] op_sel_hi:[1,0,1]
	v_pk_fma_f32 v[148:149], v[100:101], v[152:153], v[36:37] op_sel_hi:[1,0,1]
	flat_store_dwordx4 v[154:155], v[148:151] offset:512
	s_nop 1
	v_pk_fma_f32 v[150:151], v[98:99], v[152:153], v[34:35] op_sel_hi:[1,0,1]
	v_pk_fma_f32 v[148:149], v[96:97], v[152:153], v[32:33] op_sel_hi:[1,0,1]
	flat_store_dwordx4 v[154:155], v[148:151] offset:528
	s_nop 1
	v_fmamk_f32 v145, v216, 0x3a800000, v224
	v_cmp_gt_f32_e32 vcc, s33, v145
	v_mul_f32_e32 v150, 0x4b800000, v145
	v_or_b32_e32 v148, 48, v144
	v_cndmask_b32_e32 v145, v145, v150, vcc
	v_rsq_f32_e32 v145, v145
	v_ashrrev_i32_e32 v149, 31, v148
	v_lshlrev_b64 v[154:155], 10, v[148:149]
	v_lshl_add_u64 v[154:155], v[174:175], 0, v[154:155]
	v_mul_f32_e32 v150, 0x45800000, v145
	v_cndmask_b32_e32 v152, v145, v150, vcc
	v_pk_fma_f32 v[150:151], v[94:95], v[152:153], v[46:47] op_sel_hi:[1,0,1]
	v_pk_fma_f32 v[148:149], v[92:93], v[152:153], v[44:45] op_sel_hi:[1,0,1]
	flat_store_dwordx4 v[154:155], v[148:151]
	s_nop 1
	v_pk_fma_f32 v[150:151], v[90:91], v[152:153], v[42:43] op_sel_hi:[1,0,1]
	v_pk_fma_f32 v[148:149], v[88:89], v[152:153], v[40:41] op_sel_hi:[1,0,1]
	flat_store_dwordx4 v[154:155], v[148:151] offset:16
	s_nop 1
	v_pk_fma_f32 v[150:151], v[86:87], v[152:153], v[38:39] op_sel_hi:[1,0,1]
	v_pk_fma_f32 v[148:149], v[84:85], v[152:153], v[36:37] op_sel_hi:[1,0,1]
	flat_store_dwordx4 v[154:155], v[148:151] offset:512
	s_nop 1
	v_pk_fma_f32 v[150:151], v[82:83], v[152:153], v[34:35] op_sel_hi:[1,0,1]
	v_pk_fma_f32 v[148:149], v[80:81], v[152:153], v[32:33] op_sel_hi:[1,0,1]
	flat_store_dwordx4 v[154:155], v[148:151] offset:528
	s_nop 1
	v_fmamk_f32 v145, v217, 0x3a800000, v224
	v_cmp_gt_f32_e32 vcc, s33, v145
	v_mul_f32_e32 v150, 0x4b800000, v145
	v_add_u32_e32 v148, 0x80, v144
	v_cndmask_b32_e32 v145, v145, v150, vcc
	v_rsq_f32_e32 v145, v145
	v_ashrrev_i32_e32 v149, 31, v148
	v_lshlrev_b64 v[154:155], 10, v[148:149]
	v_lshl_add_u64 v[154:155], v[174:175], 0, v[154:155]
	v_mul_f32_e32 v150, 0x45800000, v145
	v_cndmask_b32_e32 v152, v145, v150, vcc
	v_pk_fma_f32 v[150:151], v[78:79], v[152:153], v[46:47] op_sel_hi:[1,0,1]
	v_pk_fma_f32 v[148:149], v[76:77], v[152:153], v[44:45] op_sel_hi:[1,0,1]
	flat_store_dwordx4 v[154:155], v[148:151]
	s_nop 1
	v_pk_fma_f32 v[150:151], v[74:75], v[152:153], v[42:43] op_sel_hi:[1,0,1]
	v_pk_fma_f32 v[148:149], v[72:73], v[152:153], v[40:41] op_sel_hi:[1,0,1]
	flat_store_dwordx4 v[154:155], v[148:151] offset:16
	s_nop 1
	v_pk_fma_f32 v[150:151], v[70:71], v[152:153], v[38:39] op_sel_hi:[1,0,1]
	v_pk_fma_f32 v[148:149], v[68:69], v[152:153], v[36:37] op_sel_hi:[1,0,1]
;     __device__ __forceinline__ void operator()(const f32x4 (&acc)[2][2][4][2], const Unit& u, int wr, int wc, int fr, int fq) const {
;     ...
;         } else if (pn == 6) {
; #pragma unroll
;             for (int ai = 0; ai < 2; ++ai)
; #pragma unroll
;                 for (int m = 0; m < 4; ++m) {
;                     const int row = pm * 256 + ai * 128 + wr * 64 + m * 16 + fr;
;                     const float rinv = rsqrtf(rowsq[row] * (1.f / DM) + EPSN);
; #pragma unroll
;                     for (int bj = 0; bj < 2; ++bj)
; #pragma unroll
;                         for (int n = 0; n < 2; ++n) *(f32x4*)(upool + (size_t)row * 256 + 128 * bj + 32 * wc + 8 * fq + 4 * n) = acc[ai][bj][m][n] * rinv + bv[bj][n];
;                 }
	flat_store_dwordx4 v[154:155], v[148:151] offset:512
	s_nop 1
	v_pk_fma_f32 v[150:151], v[66:67], v[152:153], v[34:35] op_sel_hi:[1,0,1]
	v_pk_fma_f32 v[148:149], v[64:65], v[152:153], v[32:33] op_sel_hi:[1,0,1]
	flat_store_dwordx4 v[154:155], v[148:151] offset:528
	s_nop 1
	v_fmamk_f32 v145, v218, 0x3a800000, v224
	v_cmp_gt_f32_e32 vcc, s33, v145
	v_mul_f32_e32 v150, 0x4b800000, v145
	v_add_u32_e32 v148, 0x90, v144
	v_cndmask_b32_e32 v145, v145, v150, vcc
	v_rsq_f32_e32 v145, v145
	v_ashrrev_i32_e32 v149, 31, v148
	v_lshlrev_b64 v[154:155], 10, v[148:149]
	v_lshl_add_u64 v[154:155], v[174:175], 0, v[154:155]
	v_mul_f32_e32 v150, 0x45800000, v145
	v_cndmask_b32_e32 v152, v145, v150, vcc
	v_pk_fma_f32 v[150:151], v[62:63], v[152:153], v[46:47] op_sel_hi:[1,0,1]
	v_pk_fma_f32 v[148:149], v[60:61], v[152:153], v[44:45] op_sel_hi:[1,0,1]
	flat_store_dwordx4 v[154:155], v[148:151]
	s_nop 1
	v_pk_fma_f32 v[150:151], v[58:59], v[152:153], v[42:43] op_sel_hi:[1,0,1]
	v_pk_fma_f32 v[148:149], v[56:57], v[152:153], v[40:41] op_sel_hi:[1,0,1]
	flat_store_dwordx4 v[154:155], v[148:151] offset:16
	s_nop 1
	v_pk_fma_f32 v[150:151], v[54:55], v[152:153], v[38:39] op_sel_hi:[1,0,1]
	v_pk_fma_f32 v[148:149], v[52:53], v[152:153], v[36:37] op_sel_hi:[1,0,1]
	flat_store_dwordx4 v[154:155], v[148:151] offset:512
	s_nop 1
	v_pk_fma_f32 v[150:151], v[50:51], v[152:153], v[34:35] op_sel_hi:[1,0,1]
	v_pk_fma_f32 v[148:149], v[48:49], v[152:153], v[32:33] op_sel_hi:[1,0,1]
	flat_store_dwordx4 v[154:155], v[148:151] offset:528
	s_nop 1
	v_fmamk_f32 v145, v219, 0x3a800000, v224
	v_cmp_gt_f32_e32 vcc, s33, v145
	v_mul_f32_e32 v150, 0x4b800000, v145
	v_add_u32_e32 v148, 0xa0, v144
	v_cndmask_b32_e32 v145, v145, v150, vcc
	v_rsq_f32_e32 v145, v145
	v_ashrrev_i32_e32 v149, 31, v148
	v_lshlrev_b64 v[154:155], 10, v[148:149]
	v_lshl_add_u64 v[154:155], v[174:175], 0, v[154:155]
	v_mul_f32_e32 v150, 0x45800000, v145
	v_cndmask_b32_e32 v152, v145, v150, vcc
	v_pk_fma_f32 v[150:151], v[30:31], v[152:153], v[46:47] op_sel_hi:[1,0,1]
	v_pk_fma_f32 v[148:149], v[28:29], v[152:153], v[44:45] op_sel_hi:[1,0,1]
	flat_store_dwordx4 v[154:155], v[148:151]
	v_add_u32_e32 v144, 0xb0, v144
	v_ashrrev_i32_e32 v145, 31, v144
	v_pk_fma_f32 v[150:151], v[26:27], v[152:153], v[42:43] op_sel_hi:[1,0,1]
	v_pk_fma_f32 v[148:149], v[24:25], v[152:153], v[40:41] op_sel_hi:[1,0,1]
	flat_store_dwordx4 v[154:155], v[148:151] offset:16
	s_nop 1
	v_pk_fma_f32 v[150:151], v[22:23], v[152:153], v[38:39] op_sel_hi:[1,0,1]
	v_pk_fma_f32 v[148:149], v[20:21], v[152:153], v[36:37] op_sel_hi:[1,0,1]
	flat_store_dwordx4 v[154:155], v[148:151] offset:512
	s_nop 1
	v_pk_fma_f32 v[150:151], v[18:19], v[152:153], v[34:35] op_sel_hi:[1,0,1]
	v_pk_fma_f32 v[148:149], v[16:17], v[152:153], v[32:33] op_sel_hi:[1,0,1]
	flat_store_dwordx4 v[154:155], v[148:151] offset:528
	flat_load_dword v146, v[146:147] offset:704
	s_waitcnt vmcnt(0) lgkmcnt(0)
	v_fmamk_f32 v146, v146, 0x3a800000, v224
	v_cmp_gt_f32_e32 vcc, s33, v146
	v_mul_f32_e32 v147, 0x4b800000, v146
	v_lshlrev_b64 v[150:151], 10, v[144:145]
	v_cndmask_b32_e32 v146, v146, v147, vcc
	v_rsq_f32_e32 v146, v146
	v_lshl_add_u64 v[150:151], v[174:175], 0, v[150:151]
	v_mul_f32_e32 v147, 0x45800000, v146
	v_cndmask_b32_e32 v148, v146, v147, vcc
	v_pk_fma_f32 v[146:147], v[14:15], v[148:149], v[46:47] op_sel_hi:[1,0,1]
	v_pk_fma_f32 v[144:145], v[12:13], v[148:149], v[44:45] op_sel_hi:[1,0,1]
	flat_store_dwordx4 v[150:151], v[144:147]
	s_nop 1
	v_pk_fma_f32 v[146:147], v[10:11], v[148:149], v[42:43] op_sel_hi:[1,0,1]
	v_pk_fma_f32 v[144:145], v[8:9], v[148:149], v[40:41] op_sel_hi:[1,0,1]
	flat_store_dwordx4 v[150:151], v[144:147] offset:16
	s_nop 1
	v_pk_fma_f32 v[146:147], v[6:7], v[148:149], v[38:39] op_sel_hi:[1,0,1]
	v_pk_fma_f32 v[144:145], v[4:5], v[148:149], v[36:37] op_sel_hi:[1,0,1]
	flat_store_dwordx4 v[150:151], v[144:147] offset:512
	s_nop 1
	v_pk_fma_f32 v[146:147], v[2:3], v[148:149], v[34:35] op_sel_hi:[1,0,1]
	v_pk_fma_f32 v[144:145], v[0:1], v[148:149], v[32:33] op_sel_hi:[1,0,1]
	flat_store_dwordx4 v[150:151], v[144:147] offset:528

; __device__ __forceinline__ unsigned pkbf(float lo, float hi) { return pg8::cvt_pk_bf16(lo, hi); }
;     __device__ __forceinline__ void operator()(const f32x4 (&acc)[2][2][4][2], const Unit& u, int wr, int wc, int fr, int fq) const {
;     ...
;         } else if (pn < 6) {
; #pragma unroll
;             for (int ai = 0; ai < 2; ++ai)
; #pragma unroll
;                 for (int m = 0; m < 4; ++m) {
;                     const int row = pm * 256 + ai * 128 + wr * 64 + m * 16 + fr;
;                     const float rinv = rsqrtf(rowsq[row] * (1.f / DM) + EPSN);
;                     int b, kidx;
;                     if (isctx) { const int rc = row - MLAT; b = rc >> 8; kidx = rc & 255; } else { b = row >> 13; kidx = CTXL + (row & (SEQ - 1)); }
; #pragma unroll
;                     for (int bj = 0; bj < 2; ++bj) {
;                         const f32x4 y0 = acc[ai][bj][m][0] * rinv + bv[bj][0], y1 = acc[ai][bj][m][1] * rinv + bv[bj][1];
;                         u32x4 w; w.x = pkbf(y0[0], y0[1]); w.y = pkbf(y0[2], y0[3]); w.z = pkbf(y1[0], y1[1]); w.w = pkbf(y1[2], y1[3]);
;                         const int head = 2 * (pn - 4) + bj;
;                         const size_t off = (size_t)(b * 4 + head) * (LK * 128) + (size_t)(kidx >> 6) * 8192 + (size_t)(voff(kidx & 63, 4 * wc + fq) >> 1);
;                         *(u32x4*)(Vb + off) = w;
;                     }
;                 }
.LBB0_222:
	s_andn2_b64 vcc, exec, s[0:1]
	s_cbranch_vccnz .LBB0_224
	s_lshl_b32 s25, s6, 8
	s_add_i32 s25, s25, s75
	v_or_b32_e32 v148, s25, v171
	v_ashrrev_i32_e32 v149, 31, v148
	v_lshl_add_u64 v[150:151], v[148:149], 2, s[16:17]
	flat_load_dword v144, v[150:151]
	s_lshl_b32 s7, s36, 1
	s_add_i32 s0, s25, 0xffffc000
	s_add_i32 s7, s7, -8
	s_ashr_i32 s14, s25, 13
	s_ashr_i32 s15, s0, 8
	s_and_b64 s[0:1], s[4:5], exec
	s_cselect_b32 s0, s15, s14
	s_lshl_b32 s14, s0, 2
	s_add_i32 s14, s14, s7
	s_mul_i32 s0, s14, 0x210000
	s_mul_hi_i32 s1, s14, 0x210000
	s_add_u32 s0, s72, s0
	s_addc_u32 s1, s73, s1
	s_or_b32 s14, s14, 1
	s_mul_hi_i32 s15, s14, 0x210000
	s_mul_i32 s14, s14, 0x210000
	s_add_u32 s14, s72, s14
	s_addc_u32 s15, s73, s15
	s_waitcnt vmcnt(0) lgkmcnt(0)
	v_fmamk_f32 v144, v144, 0x3a800000, v224
	v_cmp_gt_f32_e32 vcc, s33, v144
	v_mul_f32_e32 v145, 0x4b800000, v144
	s_nop 0
	v_cndmask_b32_e32 v144, v144, v145, vcc
	v_rsq_f32_e32 v144, v144
	s_nop 0
	v_mul_f32_e32 v145, 0x45800000, v144
	v_cndmask_b32_e32 v154, v144, v145, vcc
	v_bitop3_b32 v145, s25, v228, v171 bitop3:0xc8
	v_bitop3_b32 v144, s25, v227, v171 bitop3:0xc8
	v_add_u32_e32 v145, 0x100, v145
	v_cndmask_b32_e64 v144, v145, v144, s[4:5]
	v_lshrrev_b32_e32 v147, 2, v144
	v_lshlrev_b32_e32 v145, 7, v144
	v_xor_b32_e32 v147, v147, v169
	v_and_b32_e32 v145, 0x400, v145
	v_lshlrev_b32_e32 v146, 5, v144
	v_lshlrev_b32_e32 v147, 3, v147
	v_and_b32_e32 v147, 24, v147
	v_and_or_b32 v145, v146, s79, v145
	v_lshlrev_b32_e32 v144, 8, v144
	v_or3_b32 v149, v145, v147, s38
	v_and_b32_e32 v176, 0x3fc000, v144
	v_pk_fma_f32 v[146:147], v[142:143], v[154:155], v[46:47] op_sel_hi:[1,0,1]
	v_pk_fma_f32 v[144:145], v[140:141], v[154:155], v[44:45] op_sel_hi:[1,0,1]
	v_pk_fma_f32 v[152:153], v[138:139], v[154:155], v[42:43] op_sel_hi:[1,0,1]
	v_pk_fma_f32 v[156:157], v[136:137], v[154:155], v[40:41] op_sel_hi:[1,0,1]
	v_cvt_pk_bf16_f32 v144, v144, v145
	v_cvt_pk_bf16_f32 v145, v146, v147
	s_nop 0
	v_cvt_pk_bf16_f32 v146, v156, v157
	v_cvt_pk_bf16_f32 v147, v152, v153
	v_lshl_add_u64 v[156:157], s[0:1], 0, v[176:177]
	v_lshlrev_b32_e32 v152, 1, v149
	v_mov_b32_e32 v153, v177
	v_lshl_add_u64 v[156:157], v[156:157], 0, v[152:153]
	flat_store_dwordx4 v[156:157], v[144:147]
	v_pk_fma_f32 v[156:157], v[130:131], v[154:155], v[34:35] op_sel_hi:[1,0,1]
	s_nop 0
	v_pk_fma_f32 v[146:147], v[134:135], v[154:155], v[38:39] op_sel_hi:[1,0,1]
	v_pk_fma_f32 v[144:145], v[132:133], v[154:155], v[36:37] op_sel_hi:[1,0,1]
	v_pk_fma_f32 v[154:155], v[128:129], v[154:155], v[32:33] op_sel_hi:[1,0,1]
	v_cvt_pk_bf16_f32 v144, v144, v145
	v_cvt_pk_bf16_f32 v145, v146, v147
	s_nop 0
	v_cvt_pk_bf16_f32 v146, v154, v155
	v_lshl_add_u64 v[154:155], s[14:15], 0, v[176:177]
	v_lshl_add_u64 v[152:153], v[154:155], 0, v[152:153]
	v_cvt_pk_bf16_f32 v147, v156, v157
	flat_store_dwordx4 v[152:153], v[144:147]
	flat_load_dword v144, v[150:151] offset:64
	flat_load_dword v214, v[150:151] offset:128
	flat_load_dword v215, v[150:151] offset:192
	s_waitcnt vmcnt(0) lgkmcnt(0)
	v_fmamk_f32 v144, v144, 0x3a800000, v224
	v_cmp_gt_f32_e32 vcc, s33, v144
	v_mul_f32_e32 v145, 0x4b800000, v144
	s_nop 0
	v_cndmask_b32_e32 v144, v144, v145, vcc
	v_rsq_f32_e32 v144, v144
	s_nop 0
	v_mul_f32_e32 v145, 0x45800000, v144
	v_cndmask_b32_e32 v146, v144, v145, vcc
	v_bitop3_b32 v145, v148, s84, 16 bitop3:0xc8
	v_bitop3_b32 v144, v148, s95, 16 bitop3:0xc8
	v_add_u32_e32 v145, 0x100, v145
	v_cndmask_b32_e64 v144, v145, v144, s[4:5]
	v_lshrrev_b32_e32 v149, 2, v144
	v_lshlrev_b32_e32 v145, 7, v144
	v_xor_b32_e32 v149, v149, v169
	v_and_b32_e32 v145, 0xc00, v145
	v_lshlrev_b32_e32 v147, 5, v144
	v_lshlrev_b32_e32 v149, 3, v149
	v_and_b32_e32 v149, 24, v149
	v_and_or_b32 v145, v147, s79, v145
	v_or3_b32 v147, v145, v149, s38
	v_lshlrev_b32_e32 v144, 8, v144
	v_and_b32_e32 v176, 0x3fc000, v144
	v_pk_fma_f32 v[144:145], v[126:127], v[146:147], v[46:47] op_sel_hi:[1,0,1]
	v_pk_fma_f32 v[152:153], v[124:125], v[146:147], v[44:45] op_sel_hi:[1,0,1]
	v_pk_fma_f32 v[156:157], v[122:123], v[146:147], v[42:43] op_sel_hi:[1,0,1]
	v_pk_fma_f32 v[154:155], v[120:121], v[146:147], v[40:41] op_sel_hi:[1,0,1]
	v_cvt_pk_bf16_f32 v152, v152, v153
	v_cvt_pk_bf16_f32 v153, v144, v145
	v_lshlrev_b32_e32 v144, 1, v147
	v_cvt_pk_bf16_f32 v154, v154, v155
	v_cvt_pk_bf16_f32 v155, v156, v157
	v_lshl_add_u64 v[156:157], s[0:1], 0, v[176:177]
	v_mov_b32_e32 v145, v177
	v_lshl_add_u64 v[156:157], v[156:157], 0, v[144:145]
	flat_store_dwordx4 v[156:157], v[152:155]
	v_pk_fma_f32 v[156:157], v[114:115], v[146:147], v[34:35] op_sel_hi:[1,0,1]
	s_nop 0
	v_pk_fma_f32 v[154:155], v[118:119], v[146:147], v[38:39] op_sel_hi:[1,0,1]
	v_pk_fma_f32 v[152:153], v[116:117], v[146:147], v[36:37] op_sel_hi:[1,0,1]
	v_pk_fma_f32 v[146:147], v[112:113], v[146:147], v[32:33] op_sel_hi:[1,0,1]
	v_cvt_pk_bf16_f32 v152, v152, v153
	v_cvt_pk_bf16_f32 v153, v154, v155
	s_nop 0
	v_cvt_pk_bf16_f32 v154, v146, v147
	v_lshl_add_u64 v[146:147], s[14:15], 0, v[176:177]
	v_lshl_add_u64 v[144:145], v[146:147], 0, v[144:145]
	v_cvt_pk_bf16_f32 v155, v156, v157
	flat_store_dwordx4 v[144:145], v[152:155]
	s_nop 1
	v_fmamk_f32 v144, v214, 0x3a800000, v224
	v_cmp_gt_f32_e32 vcc, s33, v144
	v_mul_f32_e32 v145, 0x4b800000, v144
	s_nop 0
	v_cndmask_b32_e32 v144, v144, v145, vcc
	v_rsq_f32_e32 v144, v144
	s_nop 0
	v_mul_f32_e32 v145, 0x45800000, v144
	v_cndmask_b32_e32 v146, v144, v145, vcc
	v_bitop3_b32 v145, v148, s81, 32 bitop3:0xc8
	v_bitop3_b32 v144, v148, s80, 32 bitop3:0xc8
	v_add_u32_e32 v145, 0x100, v145
	v_cndmask_b32_e64 v144, v145, v144, s[4:5]
	v_lshrrev_b32_e32 v149, 2, v144
	v_lshlrev_b32_e32 v145, 7, v144
; __device__ __forceinline__ unsigned pkbf(float lo, float hi) { return pg8::cvt_pk_bf16(lo, hi); }
;     __device__ __forceinline__ void operator()(const f32x4 (&acc)[2][2][4][2], const Unit& u, int wr, int wc, int fr, int fq) const {
;     ...
;         } else if (pn < 6) {
; #pragma unroll
;             for (int ai = 0; ai < 2; ++ai)
; #pragma unroll
;                 for (int m = 0; m < 4; ++m) {
;                     const int row = pm * 256 + ai * 128 + wr * 64 + m * 16 + fr;
;                     const float rinv = rsqrtf(rowsq[row] * (1.f / DM) + EPSN);
;                     int b, kidx;
;                     if (isctx) { const int rc = row - MLAT; b = rc >> 8; kidx = rc & 255; } else { b = row >> 13; kidx = CTXL + (row & (SEQ - 1)); }
; #pragma unroll
;                     for (int bj = 0; bj < 2; ++bj) {
;                         const f32x4 y0 = acc[ai][bj][m][0] * rinv + bv[bj][0], y1 = acc[ai][bj][m][1] * rinv + bv[bj][1];
;                         u32x4 w; w.x = pkbf(y0[0], y0[1]); w.y = pkbf(y0[2], y0[3]); w.z = pkbf(y1[0], y1[1]); w.w = pkbf(y1[2], y1[3]);
;                         const int head = 2 * (pn - 4) + bj;
;                         const size_t off = (size_t)(b * 4 + head) * (LK * 128) + (size_t)(kidx >> 6) * 8192 + (size_t)(voff(kidx & 63, 4 * wc + fq) >> 1);
;                         *(u32x4*)(Vb + off) = w;
;                     }
;                 }
	v_xor_b32_e32 v149, v149, v169
	v_and_b32_e32 v145, 0x1400, v145
	v_lshlrev_b32_e32 v147, 5, v144
	v_lshlrev_b32_e32 v149, 3, v149
	v_and_b32_e32 v149, 24, v149
	v_and_or_b32 v145, v147, s79, v145
	v_or3_b32 v147, v145, v149, s38
	v_lshlrev_b32_e32 v144, 8, v144
	v_and_b32_e32 v176, 0x3fc000, v144
	v_pk_fma_f32 v[144:145], v[110:111], v[146:147], v[46:47] op_sel_hi:[1,0,1]
	v_pk_fma_f32 v[152:153], v[108:109], v[146:147], v[44:45] op_sel_hi:[1,0,1]
	v_pk_fma_f32 v[156:157], v[106:107], v[146:147], v[42:43] op_sel_hi:[1,0,1]
	v_pk_fma_f32 v[154:155], v[104:105], v[146:147], v[40:41] op_sel_hi:[1,0,1]
	v_cvt_pk_bf16_f32 v152, v152, v153
	v_cvt_pk_bf16_f32 v153, v144, v145
	v_lshlrev_b32_e32 v144, 1, v147
	v_cvt_pk_bf16_f32 v154, v154, v155
	v_cvt_pk_bf16_f32 v155, v156, v157
	v_lshl_add_u64 v[156:157], s[0:1], 0, v[176:177]
	v_mov_b32_e32 v145, v177
	v_lshl_add_u64 v[156:157], v[156:157], 0, v[144:145]
	flat_store_dwordx4 v[156:157], v[152:155]
	v_pk_fma_f32 v[156:157], v[98:99], v[146:147], v[34:35] op_sel_hi:[1,0,1]
	s_nop 0
	v_pk_fma_f32 v[154:155], v[102:103], v[146:147], v[38:39] op_sel_hi:[1,0,1]
	v_pk_fma_f32 v[152:153], v[100:101], v[146:147], v[36:37] op_sel_hi:[1,0,1]
	v_pk_fma_f32 v[146:147], v[96:97], v[146:147], v[32:33] op_sel_hi:[1,0,1]
	v_cvt_pk_bf16_f32 v152, v152, v153
	v_cvt_pk_bf16_f32 v153, v154, v155
	s_nop 0
	v_cvt_pk_bf16_f32 v154, v146, v147
	v_lshl_add_u64 v[146:147], s[14:15], 0, v[176:177]
	v_lshl_add_u64 v[144:145], v[146:147], 0, v[144:145]
	v_cvt_pk_bf16_f32 v155, v156, v157
	flat_store_dwordx4 v[144:145], v[152:155]
	s_nop 1
	v_fmamk_f32 v144, v215, 0x3a800000, v224
	v_cmp_gt_f32_e32 vcc, s33, v144
	v_mul_f32_e32 v145, 0x4b800000, v144
	s_nop 0
	v_cndmask_b32_e32 v144, v144, v145, vcc
	v_rsq_f32_e32 v144, v144
	s_nop 0
	v_mul_f32_e32 v145, 0x45800000, v144
	v_cndmask_b32_e32 v150, v144, v145, vcc
	v_bitop3_b32 v145, v148, s68, 48 bitop3:0xc8
	v_bitop3_b32 v144, v148, s48, 48 bitop3:0xc8
	v_add_u32_e32 v145, 0x100, v145
	v_cndmask_b32_e64 v144, v145, v144, s[4:5]
	v_lshrrev_b32_e32 v147, 2, v144
	v_lshlrev_b32_e32 v145, 7, v144
	v_xor_b32_e32 v147, v147, v169
	v_and_b32_e32 v145, 0x1c00, v145
	v_lshlrev_b32_e32 v146, 5, v144
	v_lshlrev_b32_e32 v147, 3, v147
	v_and_b32_e32 v147, 24, v147
	v_and_or_b32 v145, v146, s79, v145
	v_or3_b32 v151, v145, v147, s38
	v_lshlrev_b32_e32 v144, 8, v144
	v_and_b32_e32 v176, 0x3fc000, v144
	v_pk_fma_f32 v[146:147], v[94:95], v[150:151], v[46:47] op_sel_hi:[1,0,1]
	v_pk_fma_f32 v[144:145], v[92:93], v[150:151], v[44:45] op_sel_hi:[1,0,1]
	v_pk_fma_f32 v[148:149], v[90:91], v[150:151], v[42:43] op_sel_hi:[1,0,1]
	v_pk_fma_f32 v[152:153], v[88:89], v[150:151], v[40:41] op_sel_hi:[1,0,1]
	v_cvt_pk_bf16_f32 v144, v144, v145
	v_cvt_pk_bf16_f32 v145, v146, v147
	s_nop 0
	v_cvt_pk_bf16_f32 v146, v152, v153
	v_cvt_pk_bf16_f32 v147, v148, v149
	v_lshl_add_u64 v[148:149], s[0:1], 0, v[176:177]
	v_lshlrev_b32_e32 v152, 1, v151
	v_mov_b32_e32 v153, v177
	v_lshl_add_u64 v[148:149], v[148:149], 0, v[152:153]
	flat_store_dwordx4 v[148:149], v[144:147]
	v_pk_fma_f32 v[148:149], v[82:83], v[150:151], v[34:35] op_sel_hi:[1,0,1]
	s_add_i32 s0, s25, 0x80
	v_pk_fma_f32 v[146:147], v[86:87], v[150:151], v[38:39] op_sel_hi:[1,0,1]
	v_pk_fma_f32 v[144:145], v[84:85], v[150:151], v[36:37] op_sel_hi:[1,0,1]
	v_pk_fma_f32 v[150:151], v[80:81], v[150:151], v[32:33] op_sel_hi:[1,0,1]
	v_cvt_pk_bf16_f32 v144, v144, v145
	v_cvt_pk_bf16_f32 v145, v146, v147
	s_addk_i32 s25, 0xc080
	v_cvt_pk_bf16_f32 v146, v150, v151
	v_cvt_pk_bf16_f32 v147, v148, v149
	v_lshl_add_u64 v[148:149], s[14:15], 0, v[176:177]
	v_lshl_add_u64 v[148:149], v[148:149], 0, v[152:153]
	flat_store_dwordx4 v[148:149], v[144:147]
	v_or_b32_e32 v148, s0, v171
	v_ashrrev_i32_e32 v149, 31, v148
	v_lshl_add_u64 v[150:151], v[148:149], 2, s[16:17]
	flat_load_dword v144, v[150:151]
	flat_load_dword v214, v[150:151] offset:64
	flat_load_dword v215, v[150:151] offset:128
	flat_load_dword v216, v[150:151] offset:192
	s_ashr_i32 s14, s0, 13
	s_ashr_i32 s15, s25, 8
	s_waitcnt vmcnt(0) lgkmcnt(0)
	v_fmamk_f32 v144, v144, 0x3a800000, v224
	v_cmp_gt_f32_e32 vcc, s33, v144
	v_mul_f32_e32 v145, 0x4b800000, v144
	s_nop 0
	v_cndmask_b32_e32 v144, v144, v145, vcc
	v_rsq_f32_e32 v144, v144
	s_nop 0
	v_mul_f32_e32 v145, 0x45800000, v144
	v_cndmask_b32_e32 v154, v144, v145, vcc
	v_bitop3_b32 v145, s0, v228, v171 bitop3:0xc8
	v_bitop3_b32 v144, s0, v227, v171 bitop3:0xc8
	v_add_u32_e32 v145, 0x100, v145
	s_and_b64 s[0:1], s[4:5], exec
	s_cselect_b32 s0, s15, s14
	v_cndmask_b32_e64 v144, v145, v144, s[4:5]
	s_lshl_b32 s0, s0, 2
	v_lshrrev_b32_e32 v147, 2, v144
	s_add_i32 s7, s0, s7
	v_lshlrev_b32_e32 v145, 7, v144
	v_xor_b32_e32 v147, v147, v169
	v_and_b32_e32 v145, 0x400, v145
	v_lshlrev_b32_e32 v146, 5, v144
	v_lshlrev_b32_e32 v147, 3, v147
	s_mul_i32 s0, s7, 0x210000
	v_and_b32_e32 v147, 24, v147
	v_and_or_b32 v145, v146, s79, v145
	v_lshlrev_b32_e32 v144, 8, v144
	s_mul_hi_i32 s1, s7, 0x210000
	s_add_u32 s0, s72, s0
	v_or3_b32 v149, v145, v147, s38
	v_and_b32_e32 v176, 0x3fc000, v144
	v_pk_fma_f32 v[146:147], v[78:79], v[154:155], v[46:47] op_sel_hi:[1,0,1]
	v_pk_fma_f32 v[144:145], v[76:77], v[154:155], v[44:45] op_sel_hi:[1,0,1]
	v_pk_fma_f32 v[152:153], v[74:75], v[154:155], v[42:43] op_sel_hi:[1,0,1]
	v_pk_fma_f32 v[156:157], v[72:73], v[154:155], v[40:41] op_sel_hi:[1,0,1]
	s_addc_u32 s1, s73, s1
	s_or_b32 s7, s7, 1
	v_cvt_pk_bf16_f32 v144, v144, v145
	v_cvt_pk_bf16_f32 v145, v146, v147
	v_cvt_pk_bf16_f32 v146, v156, v157
	v_cvt_pk_bf16_f32 v147, v152, v153
	v_lshl_add_u64 v[156:157], s[0:1], 0, v[176:177]
	v_lshlrev_b32_e32 v152, 1, v149
; __device__ __forceinline__ unsigned pkbf(float lo, float hi) { return pg8::cvt_pk_bf16(lo, hi); }
;     __device__ __forceinline__ void operator()(const f32x4 (&acc)[2][2][4][2], const Unit& u, int wr, int wc, int fr, int fq) const {
;     ...
;         } else if (pn < 6) {
; #pragma unroll
;             for (int ai = 0; ai < 2; ++ai)
; #pragma unroll
;                 for (int m = 0; m < 4; ++m) {
;                     const int row = pm * 256 + ai * 128 + wr * 64 + m * 16 + fr;
;                     const float rinv = rsqrtf(rowsq[row] * (1.f / DM) + EPSN);
;                     int b, kidx;
;                     if (isctx) { const int rc = row - MLAT; b = rc >> 8; kidx = rc & 255; } else { b = row >> 13; kidx = CTXL + (row & (SEQ - 1)); }
; #pragma unroll
;                     for (int bj = 0; bj < 2; ++bj) {
;                         const f32x4 y0 = acc[ai][bj][m][0] * rinv + bv[bj][0], y1 = acc[ai][bj][m][1] * rinv + bv[bj][1];
;                         u32x4 w; w.x = pkbf(y0[0], y0[1]); w.y = pkbf(y0[2], y0[3]); w.z = pkbf(y1[0], y1[1]); w.w = pkbf(y1[2], y1[3]);
;                         const int head = 2 * (pn - 4) + bj;
;                         const size_t off = (size_t)(b * 4 + head) * (LK * 128) + (size_t)(kidx >> 6) * 8192 + (size_t)(voff(kidx & 63, 4 * wc + fq) >> 1);
;                         *(u32x4*)(Vb + off) = w;
;                     }
;                 }
	v_mov_b32_e32 v153, v177
	s_mul_hi_i32 s15, s7, 0x210000
	s_mul_i32 s7, s7, 0x210000
	v_lshl_add_u64 v[156:157], v[156:157], 0, v[152:153]
	s_add_u32 s14, s72, s7
	flat_store_dwordx4 v[156:157], v[144:147]
	v_pk_fma_f32 v[156:157], v[66:67], v[154:155], v[34:35] op_sel_hi:[1,0,1]
	s_addc_u32 s15, s73, s15
	v_pk_fma_f32 v[146:147], v[70:71], v[154:155], v[38:39] op_sel_hi:[1,0,1]
	v_pk_fma_f32 v[144:145], v[68:69], v[154:155], v[36:37] op_sel_hi:[1,0,1]
	v_pk_fma_f32 v[154:155], v[64:65], v[154:155], v[32:33] op_sel_hi:[1,0,1]
	v_cvt_pk_bf16_f32 v144, v144, v145
	v_cvt_pk_bf16_f32 v145, v146, v147
	s_nop 0
	v_cvt_pk_bf16_f32 v146, v154, v155
	v_lshl_add_u64 v[154:155], s[14:15], 0, v[176:177]
	v_lshl_add_u64 v[152:153], v[154:155], 0, v[152:153]
	v_cvt_pk_bf16_f32 v147, v156, v157
	flat_store_dwordx4 v[152:153], v[144:147]
	s_nop 1
	v_fmamk_f32 v144, v214, 0x3a800000, v224
	v_cmp_gt_f32_e32 vcc, s33, v144
	v_mul_f32_e32 v145, 0x4b800000, v144
	s_nop 0
	v_cndmask_b32_e32 v144, v144, v145, vcc
	v_rsq_f32_e32 v144, v144
	s_nop 0
	v_mul_f32_e32 v145, 0x45800000, v144
	v_cndmask_b32_e32 v146, v144, v145, vcc
	v_bitop3_b32 v145, v148, s84, 16 bitop3:0xc8
	v_bitop3_b32 v144, v148, s95, 16 bitop3:0xc8
	v_add_u32_e32 v145, 0x100, v145
	v_cndmask_b32_e64 v144, v145, v144, s[4:5]
	v_lshrrev_b32_e32 v149, 2, v144
	v_lshlrev_b32_e32 v145, 7, v144
	v_xor_b32_e32 v149, v149, v169
	v_and_b32_e32 v145, 0xc00, v145
	v_lshlrev_b32_e32 v147, 5, v144
	v_lshlrev_b32_e32 v149, 3, v149
	v_and_b32_e32 v149, 24, v149
	v_and_or_b32 v145, v147, s79, v145
	v_or3_b32 v147, v145, v149, s38
	v_lshlrev_b32_e32 v144, 8, v144
	v_and_b32_e32 v176, 0x3fc000, v144
	v_pk_fma_f32 v[144:145], v[62:63], v[146:147], v[46:47] op_sel_hi:[1,0,1]
	v_pk_fma_f32 v[152:153], v[60:61], v[146:147], v[44:45] op_sel_hi:[1,0,1]
	v_pk_fma_f32 v[156:157], v[58:59], v[146:147], v[42:43] op_sel_hi:[1,0,1]
	v_pk_fma_f32 v[154:155], v[56:57], v[146:147], v[40:41] op_sel_hi:[1,0,1]
	v_cvt_pk_bf16_f32 v152, v152, v153
	v_cvt_pk_bf16_f32 v153, v144, v145
	v_lshlrev_b32_e32 v144, 1, v147
	v_cvt_pk_bf16_f32 v154, v154, v155
	v_cvt_pk_bf16_f32 v155, v156, v157
	v_lshl_add_u64 v[156:157], s[0:1], 0, v[176:177]
	v_mov_b32_e32 v145, v177
	v_lshl_add_u64 v[156:157], v[156:157], 0, v[144:145]
	flat_store_dwordx4 v[156:157], v[152:155]
	v_pk_fma_f32 v[156:157], v[50:51], v[146:147], v[34:35] op_sel_hi:[1,0,1]
	s_nop 0
	v_pk_fma_f32 v[154:155], v[54:55], v[146:147], v[38:39] op_sel_hi:[1,0,1]
	v_pk_fma_f32 v[152:153], v[52:53], v[146:147], v[36:37] op_sel_hi:[1,0,1]
	v_pk_fma_f32 v[146:147], v[48:49], v[146:147], v[32:33] op_sel_hi:[1,0,1]
	v_cvt_pk_bf16_f32 v152, v152, v153
	v_cvt_pk_bf16_f32 v153, v154, v155
	s_nop 0
	v_cvt_pk_bf16_f32 v154, v146, v147
	v_lshl_add_u64 v[146:147], s[14:15], 0, v[176:177]
	v_lshl_add_u64 v[144:145], v[146:147], 0, v[144:145]
	v_cvt_pk_bf16_f32 v155, v156, v157
	flat_store_dwordx4 v[144:145], v[152:155]
	s_nop 1
	v_fmamk_f32 v144, v215, 0x3a800000, v224
	v_cmp_gt_f32_e32 vcc, s33, v144
	v_mul_f32_e32 v145, 0x4b800000, v144
	s_nop 0
	v_cndmask_b32_e32 v144, v144, v145, vcc
	v_rsq_f32_e32 v144, v144
	s_nop 0
	v_mul_f32_e32 v145, 0x45800000, v144
	v_cndmask_b32_e32 v146, v144, v145, vcc
	v_bitop3_b32 v145, v148, s81, 32 bitop3:0xc8
	v_bitop3_b32 v144, v148, s80, 32 bitop3:0xc8
	v_add_u32_e32 v145, 0x100, v145
	v_cndmask_b32_e64 v144, v145, v144, s[4:5]
	v_lshrrev_b32_e32 v149, 2, v144
	v_lshlrev_b32_e32 v145, 7, v144
	v_xor_b32_e32 v149, v149, v169
	v_and_b32_e32 v145, 0x1400, v145
	v_lshlrev_b32_e32 v147, 5, v144
; __device__ __forceinline__ unsigned pkbf(float lo, float hi) { return pg8::cvt_pk_bf16(lo, hi); }
;     __device__ __forceinline__ void operator()(const f32x4 (&acc)[2][2][4][2], const Unit& u, int wr, int wc, int fr, int fq) const {
;     ...
;         } else if (pn < 6) {
; #pragma unroll
;             for (int ai = 0; ai < 2; ++ai)
; #pragma unroll
;                 for (int m = 0; m < 4; ++m) {
;                     const int row = pm * 256 + ai * 128 + wr * 64 + m * 16 + fr;
;                     const float rinv = rsqrtf(rowsq[row] * (1.f / DM) + EPSN);
;                     int b, kidx;
;                     if (isctx) { const int rc = row - MLAT; b = rc >> 8; kidx = rc & 255; } else { b = row >> 13; kidx = CTXL + (row & (SEQ - 1)); }
; #pragma unroll
;                     for (int bj = 0; bj < 2; ++bj) {
;                         const f32x4 y0 = acc[ai][bj][m][0] * rinv + bv[bj][0], y1 = acc[ai][bj][m][1] * rinv + bv[bj][1];
;                         u32x4 w; w.x = pkbf(y0[0], y0[1]); w.y = pkbf(y0[2], y0[3]); w.z = pkbf(y1[0], y1[1]); w.w = pkbf(y1[2], y1[3]);
;                         const int head = 2 * (pn - 4) + bj;
;                         const size_t off = (size_t)(b * 4 + head) * (LK * 128) + (size_t)(kidx >> 6) * 8192 + (size_t)(voff(kidx & 63, 4 * wc + fq) >> 1);
;                         *(u32x4*)(Vb + off) = w;
;                     }
;                 }
	v_lshlrev_b32_e32 v149, 3, v149
	v_and_b32_e32 v149, 24, v149
	v_and_or_b32 v145, v147, s79, v145
	v_or3_b32 v147, v145, v149, s38
	v_lshlrev_b32_e32 v144, 8, v144
	v_and_b32_e32 v176, 0x3fc000, v144
	v_pk_fma_f32 v[144:145], v[30:31], v[146:147], v[46:47] op_sel_hi:[1,0,1]
	v_pk_fma_f32 v[152:153], v[28:29], v[146:147], v[44:45] op_sel_hi:[1,0,1]
	v_pk_fma_f32 v[156:157], v[26:27], v[146:147], v[42:43] op_sel_hi:[1,0,1]
	v_pk_fma_f32 v[154:155], v[24:25], v[146:147], v[40:41] op_sel_hi:[1,0,1]
	v_cvt_pk_bf16_f32 v152, v152, v153
	v_cvt_pk_bf16_f32 v153, v144, v145
	v_lshlrev_b32_e32 v144, 1, v147
	v_cvt_pk_bf16_f32 v154, v154, v155
	v_cvt_pk_bf16_f32 v155, v156, v157
	v_lshl_add_u64 v[156:157], s[0:1], 0, v[176:177]
	v_mov_b32_e32 v145, v177
	v_lshl_add_u64 v[156:157], v[156:157], 0, v[144:145]
	flat_store_dwordx4 v[156:157], v[152:155]
	v_pk_fma_f32 v[156:157], v[18:19], v[146:147], v[34:35] op_sel_hi:[1,0,1]
	s_nop 0
	v_pk_fma_f32 v[154:155], v[22:23], v[146:147], v[38:39] op_sel_hi:[1,0,1]
	v_pk_fma_f32 v[152:153], v[20:21], v[146:147], v[36:37] op_sel_hi:[1,0,1]
	v_pk_fma_f32 v[146:147], v[16:17], v[146:147], v[32:33] op_sel_hi:[1,0,1]
	v_cvt_pk_bf16_f32 v152, v152, v153
	v_cvt_pk_bf16_f32 v153, v154, v155
	s_nop 0
	v_cvt_pk_bf16_f32 v154, v146, v147
	v_lshl_add_u64 v[146:147], s[14:15], 0, v[176:177]
	v_lshl_add_u64 v[144:145], v[146:147], 0, v[144:145]
	v_cvt_pk_bf16_f32 v155, v156, v157
	flat_store_dwordx4 v[144:145], v[152:155]
	s_nop 1
	v_fmamk_f32 v144, v216, 0x3a800000, v224
	v_cmp_gt_f32_e32 vcc, s33, v144
	v_mul_f32_e32 v145, 0x4b800000, v144
	s_nop 0
	v_cndmask_b32_e32 v144, v144, v145, vcc
	v_rsq_f32_e32 v144, v144
	s_nop 0
	v_mul_f32_e32 v145, 0x45800000, v144
	v_cndmask_b32_e32 v150, v144, v145, vcc
	v_bitop3_b32 v145, v148, s68, 48 bitop3:0xc8
	v_bitop3_b32 v144, v148, s48, 48 bitop3:0xc8
	v_add_u32_e32 v145, 0x100, v145
	v_cndmask_b32_e64 v144, v145, v144, s[4:5]
	v_lshrrev_b32_e32 v147, 2, v144
	v_lshlrev_b32_e32 v145, 7, v144
	v_xor_b32_e32 v147, v147, v169
	v_and_b32_e32 v145, 0x1c00, v145
	v_lshlrev_b32_e32 v146, 5, v144
	v_lshlrev_b32_e32 v147, 3, v147
	v_and_b32_e32 v147, 24, v147
	v_and_or_b32 v145, v146, s79, v145
	v_or3_b32 v151, v145, v147, s38
	v_lshlrev_b32_e32 v144, 8, v144
	v_and_b32_e32 v176, 0x3fc000, v144
	v_pk_fma_f32 v[144:145], v[14:15], v[150:151], v[46:47] op_sel_hi:[1,0,1]
	v_pk_fma_f32 v[146:147], v[12:13], v[150:151], v[44:45] op_sel_hi:[1,0,1]
	v_pk_fma_f32 v[152:153], v[10:11], v[150:151], v[42:43] op_sel_hi:[1,0,1]
	v_pk_fma_f32 v[148:149], v[8:9], v[150:151], v[40:41] op_sel_hi:[1,0,1]
	v_cvt_pk_bf16_f32 v146, v146, v147
	v_cvt_pk_bf16_f32 v147, v144, v145
	v_lshlrev_b32_e32 v144, 1, v151
	v_cvt_pk_bf16_f32 v148, v148, v149
	v_cvt_pk_bf16_f32 v149, v152, v153
	v_lshl_add_u64 v[152:153], s[0:1], 0, v[176:177]
	v_mov_b32_e32 v145, v177
	v_lshl_add_u64 v[152:153], v[152:153], 0, v[144:145]
	flat_store_dwordx4 v[152:153], v[146:149]
	v_pk_fma_f32 v[152:153], v[2:3], v[150:151], v[34:35] op_sel_hi:[1,0,1]
	s_nop 0
	v_pk_fma_f32 v[148:149], v[6:7], v[150:151], v[38:39] op_sel_hi:[1,0,1]
	v_pk_fma_f32 v[146:147], v[4:5], v[150:151], v[36:37] op_sel_hi:[1,0,1]
	v_pk_fma_f32 v[150:151], v[0:1], v[150:151], v[32:33] op_sel_hi:[1,0,1]
	v_cvt_pk_bf16_f32 v146, v146, v147
	v_cvt_pk_bf16_f32 v147, v148, v149
	s_nop 0
	v_cvt_pk_bf16_f32 v148, v150, v151
	v_lshl_add_u64 v[150:151], s[14:15], 0, v[176:177]
	v_lshl_add_u64 v[144:145], v[150:151], 0, v[144:145]
	v_cvt_pk_bf16_f32 v149, v152, v153
	flat_store_dwordx4 v[144:145], v[146:149]

; __device__ __forceinline__ float sigm(float v) { return __builtin_amdgcn_rcpf(1.f + __builtin_amdgcn_exp2f(-1.4426950408889634f * v)); }
;     __device__ __forceinline__ void operator()(const f32x4 (&acc)[2][2][4][2], const Unit& u, int wr, int wc, int fr, int fq) const {
;     ...
;         const int cb = pn * 256 + wc * 32 + 8 * fq;
;         f32x4 bv[2][2];
; #pragma unroll
;         for (int bj = 0; bj < 2; ++bj)
; #pragma unroll
;             for (int n = 0; n < 2; ++n) bv[bj][n] = *(const f32x4*)(bias + v * INW + cb + 128 * bj + 4 * n);
;     ...
;             const int ch0 = 128 * (pn - 7) + 32 * wc + 8 * fq;
; #pragma unroll
;             for (int ai = 0; ai < 2; ++ai)
; #pragma unroll
;                 for (int m = 0; m < 4; ++m) {
;                     const int row = pm * 256 + ai * 128 + wr * 64 + m * 16 + fr;
;                     const float rinv = rsqrtf(rowsq[row] * (1.f / DM) + EPSN);
; #pragma unroll
;                     for (int n = 0; n < 2; ++n) {
;                         const f32x4 a = acc[ai][0][m][n] * rinv + bv[0][n], g = acc[ai][1][m][n] * rinv + bv[1][n];
;                         f32x4 o;
; #pragma unroll
;                         for (int j = 0; j < 4; ++j) o[j] = a[j] * sigm(g[j]);
;                         *(f32x4*)(uconv + (size_t)row * 256 + ch0 + 4 * n) = o;
;                     }
.LBB0_319:
	s_min_i32 s0, s66, 64
	s_lshr_b32 s0, s0, 5
	s_mulk_i32 s0, 0x900
	s_ashr_i32 s1, s0, 31
	s_lshl_b64 s[0:1], s[0:1], 2
	v_lshl_or_b32 v32, s67, 8, v172
	s_add_u32 s0, s43, s0
	s_addc_u32 s1, s44, s1
	v_ashrrev_i32_e32 v33, 31, v32
	v_lshl_add_u64 v[32:33], v[32:33], 2, s[0:1]
	flat_load_dwordx4 v[52:55], v[32:33]
	flat_load_dwordx4 v[48:51], v[32:33] offset:16
	flat_load_dwordx4 v[36:39], v[32:33] offset:512
	s_nop 0
	flat_load_dwordx4 v[32:35], v[32:33] offset:528
	s_cmp_gt_u32 s67, 5
	s_mov_b64 s[0:1], -1
	s_cbranch_scc0 .LBB0_326
	s_cmp_lg_u32 s67, 6
	v_lshl_add_u32 v158, s66, 8, v170
	s_cbranch_scc0 .LBB0_322
	v_ashrrev_i32_e32 v159, 31, v158
	v_lshl_add_u64 v[160:161], v[158:159], 2, s[12:13]
	flat_load_dword v162, v[160:161]
	flat_load_dword v214, v[160:161] offset:64
	flat_load_dword v215, v[160:161] offset:128
	flat_load_dword v216, v[160:161] offset:192
	flat_load_dword v217, v[160:161] offset:512
	flat_load_dword v218, v[160:161] offset:576
	flat_load_dword v219, v[160:161] offset:640
	flat_load_dword v220, v[160:161] offset:704
	v_lshl_add_u32 v176, s67, 7, v173
	s_mov_b64 s[0:1], 0
	s_waitcnt vmcnt(0) lgkmcnt(0)
	v_fmamk_f32 v162, v162, 0x3a800000, v224
	v_cmp_gt_f32_e32 vcc, s33, v162
	v_mul_f32_e32 v163, 0x4b800000, v162
	s_nop 0
	v_cndmask_b32_e32 v162, v162, v163, vcc
	v_rsq_f32_e32 v162, v162
	s_nop 0
	v_mul_f32_e32 v163, 0x45800000, v162
	v_cndmask_b32_e32 v164, v162, v163, vcc
	v_lshlrev_b64 v[162:163], 10, v[158:159]
	v_fma_f32 v159, v132, v164, v36
	v_mul_f32_e32 v159, 0xbfb8aa3b, v159
	v_exp_f32_e32 v159, v159
	v_pk_fma_f32 v[186:187], v[140:141], v[164:165], v[52:53] op_sel_hi:[1,0,1]
	v_pk_fma_f32 v[184:185], v[142:143], v[164:165], v[54:55] op_sel_hi:[1,0,1]
	v_add_f32_e32 v159, 1.0, v159
	v_rcp_f32_e32 v166, v159
	v_fma_f32 v159, v133, v164, v37
	v_mul_f32_e32 v159, 0xbfb8aa3b, v159
	v_exp_f32_e32 v159, v159
	s_nop 0
	v_add_f32_e32 v159, 1.0, v159
	v_rcp_f32_e32 v167, v159
	v_fma_f32 v159, v134, v164, v38
	v_mul_f32_e32 v159, 0xbfb8aa3b, v159
	v_exp_f32_e32 v159, v159
	s_nop 0
	v_add_f32_e32 v159, 1.0, v159
	v_rcp_f32_e32 v182, v159
	v_fma_f32 v159, v135, v164, v39
	v_mul_f32_e32 v159, 0xbfb8aa3b, v159
	v_exp_f32_e32 v159, v159
	s_nop 0
	v_add_f32_e32 v159, 1.0, v159
	v_rcp_f32_e32 v183, v159
	v_fma_f32 v159, v128, v164, v32
	v_mul_f32_e32 v159, 0xbfb8aa3b, v159
	v_exp_f32_e32 v159, v159
	v_pk_mul_f32 v[184:185], v[184:185], v[182:183]
	v_pk_mul_f32 v[182:183], v[186:187], v[166:167]
	v_lshl_add_u64 v[166:167], s[16:17], 0, v[162:163]
	v_lshlrev_b64 v[162:163], 2, v[176:177]
	v_lshl_add_u64 v[166:167], v[166:167], 0, v[162:163]
	v_add_f32_e32 v159, 1.0, v159
	flat_store_dwordx4 v[166:167], v[182:185]
	v_pk_fma_f32 v[186:187], v[136:137], v[164:165], v[48:49] op_sel_hi:[1,0,1]
	s_nop 0
	v_rcp_f32_e32 v182, v159
	v_fma_f32 v159, v129, v164, v33
	v_mul_f32_e32 v159, 0xbfb8aa3b, v159
	v_exp_f32_e32 v159, v159
	s_nop 0
	v_add_f32_e32 v159, 1.0, v159
	v_rcp_f32_e32 v183, v159
	v_fma_f32 v159, v130, v164, v34
	v_mul_f32_e32 v159, 0xbfb8aa3b, v159
	v_exp_f32_e32 v159, v159
	v_pk_mul_f32 v[182:183], v[186:187], v[182:183]
	v_add_f32_e32 v159, 1.0, v159
	v_rcp_f32_e32 v184, v159
	v_fma_f32 v159, v131, v164, v35
	v_mul_f32_e32 v159, 0xbfb8aa3b, v159
	v_exp_f32_e32 v159, v159
	v_pk_fma_f32 v[164:165], v[138:139], v[164:165], v[50:51] op_sel_hi:[1,0,1]
	v_add_f32_e32 v159, 1.0, v159
	v_rcp_f32_e32 v185, v159
	s_nop 0
	v_pk_mul_f32 v[184:185], v[164:165], v[184:185]
	flat_store_dwordx4 v[166:167], v[182:185] offset:16
	s_nop 1
	v_or_b32_e32 v164, 16, v158
	v_ashrrev_i32_e32 v165, 31, v164
	v_lshlrev_b64 v[164:165], 10, v[164:165]
	v_lshl_add_u64 v[164:165], s[16:17], 0, v[164:165]
	v_lshl_add_u64 v[164:165], v[164:165], 0, v[162:163]
	v_fmamk_f32 v159, v214, 0x3a800000, v224
	v_cmp_gt_f32_e32 vcc, s33, v159
	v_mul_f32_e32 v166, 0x4b800000, v159
	s_nop 0
	v_cndmask_b32_e32 v159, v159, v166, vcc
	v_rsq_f32_e32 v159, v159
	s_nop 0
	v_mul_f32_e32 v166, 0x45800000, v159
	v_cndmask_b32_e32 v166, v159, v166, vcc
	v_fma_f32 v159, v116, v166, v36
	v_mul_f32_e32 v159, 0xbfb8aa3b, v159
	v_exp_f32_e32 v159, v159
	v_pk_fma_f32 v[186:187], v[124:125], v[166:167], v[52:53] op_sel_hi:[1,0,1]
	v_pk_fma_f32 v[188:189], v[126:127], v[166:167], v[54:55] op_sel_hi:[1,0,1]
	v_add_f32_e32 v159, 1.0, v159
	v_rcp_f32_e32 v182, v159
	v_fma_f32 v159, v117, v166, v37
	v_mul_f32_e32 v159, 0xbfb8aa3b, v159
	v_exp_f32_e32 v159, v159
	s_nop 0
	v_add_f32_e32 v159, 1.0, v159
	v_rcp_f32_e32 v183, v159
	v_fma_f32 v159, v118, v166, v38
	v_mul_f32_e32 v159, 0xbfb8aa3b, v159
	v_exp_f32_e32 v159, v159
	v_pk_mul_f32 v[182:183], v[186:187], v[182:183]
	v_pk_fma_f32 v[186:187], v[120:121], v[166:167], v[48:49] op_sel_hi:[1,0,1]
	v_add_f32_e32 v159, 1.0, v159
	v_rcp_f32_e32 v184, v159
	v_fma_f32 v159, v119, v166, v39
	v_mul_f32_e32 v159, 0xbfb8aa3b, v159
	v_exp_f32_e32 v159, v159
	s_nop 0
	v_add_f32_e32 v159, 1.0, v159
	v_rcp_f32_e32 v185, v159
	v_fma_f32 v159, v112, v166, v32
	v_mul_f32_e32 v159, 0xbfb8aa3b, v159
	v_exp_f32_e32 v159, v159
	v_pk_mul_f32 v[184:185], v[188:189], v[184:185]
	flat_store_dwordx4 v[164:165], v[182:185]
	v_add_f32_e32 v159, 1.0, v159
	s_nop 0
	v_rcp_f32_e32 v182, v159
	v_fma_f32 v159, v113, v166, v33
	v_mul_f32_e32 v159, 0xbfb8aa3b, v159
	v_exp_f32_e32 v159, v159
	s_nop 0
	v_add_f32_e32 v159, 1.0, v159
	v_rcp_f32_e32 v183, v159
	v_fma_f32 v159, v114, v166, v34
	v_mul_f32_e32 v159, 0xbfb8aa3b, v159
	v_exp_f32_e32 v159, v159
	v_pk_mul_f32 v[182:183], v[186:187], v[182:183]
	v_add_f32_e32 v159, 1.0, v159
	v_rcp_f32_e32 v184, v159
	v_fma_f32 v159, v115, v166, v35
	v_mul_f32_e32 v159, 0xbfb8aa3b, v159
	v_exp_f32_e32 v159, v159
; __device__ __forceinline__ float sigm(float v) { return __builtin_amdgcn_rcpf(1.f + __builtin_amdgcn_exp2f(-1.4426950408889634f * v)); }
;     __device__ __forceinline__ void operator()(const f32x4 (&acc)[2][2][4][2], const Unit& u, int wr, int wc, int fr, int fq) const {
;     ...
;             const int ch0 = 128 * (pn - 7) + 32 * wc + 8 * fq;
; #pragma unroll
;             for (int ai = 0; ai < 2; ++ai)
; #pragma unroll
;                 for (int m = 0; m < 4; ++m) {
;                     const int row = pm * 256 + ai * 128 + wr * 64 + m * 16 + fr;
;                     const float rinv = rsqrtf(rowsq[row] * (1.f / DM) + EPSN);
; #pragma unroll
;                     for (int n = 0; n < 2; ++n) {
;                         const f32x4 a = acc[ai][0][m][n] * rinv + bv[0][n], g = acc[ai][1][m][n] * rinv + bv[1][n];
;                         f32x4 o;
; #pragma unroll
;                         for (int j = 0; j < 4; ++j) o[j] = a[j] * sigm(g[j]);
;                         *(f32x4*)(uconv + (size_t)row * 256 + ch0 + 4 * n) = o;
;                     }
	v_pk_fma_f32 v[166:167], v[122:123], v[166:167], v[50:51] op_sel_hi:[1,0,1]
	v_add_f32_e32 v159, 1.0, v159
	v_rcp_f32_e32 v185, v159
	s_nop 0
	v_pk_mul_f32 v[184:185], v[166:167], v[184:185]
	flat_store_dwordx4 v[164:165], v[182:185] offset:16
	s_nop 1
	v_or_b32_e32 v164, 32, v158
	v_ashrrev_i32_e32 v165, 31, v164
	v_lshlrev_b64 v[164:165], 10, v[164:165]
	v_lshl_add_u64 v[164:165], s[16:17], 0, v[164:165]
	v_lshl_add_u64 v[164:165], v[164:165], 0, v[162:163]
	v_fmamk_f32 v159, v215, 0x3a800000, v224
	v_cmp_gt_f32_e32 vcc, s33, v159
	v_mul_f32_e32 v166, 0x4b800000, v159
	s_nop 0
	v_cndmask_b32_e32 v159, v159, v166, vcc
	v_rsq_f32_e32 v159, v159
	s_nop 0
	v_mul_f32_e32 v166, 0x45800000, v159
	v_cndmask_b32_e32 v166, v159, v166, vcc
	v_fma_f32 v159, v100, v166, v36
	v_mul_f32_e32 v159, 0xbfb8aa3b, v159
	v_exp_f32_e32 v159, v159
	v_pk_fma_f32 v[186:187], v[108:109], v[166:167], v[52:53] op_sel_hi:[1,0,1]
	v_pk_fma_f32 v[188:189], v[110:111], v[166:167], v[54:55] op_sel_hi:[1,0,1]
	v_add_f32_e32 v159, 1.0, v159
	v_rcp_f32_e32 v182, v159
	v_fma_f32 v159, v101, v166, v37
	v_mul_f32_e32 v159, 0xbfb8aa3b, v159
	v_exp_f32_e32 v159, v159
	s_nop 0
	v_add_f32_e32 v159, 1.0, v159
	v_rcp_f32_e32 v183, v159
	v_fma_f32 v159, v102, v166, v38
	v_mul_f32_e32 v159, 0xbfb8aa3b, v159
	v_exp_f32_e32 v159, v159
	v_pk_mul_f32 v[182:183], v[186:187], v[182:183]
	v_pk_fma_f32 v[186:187], v[104:105], v[166:167], v[48:49] op_sel_hi:[1,0,1]
	v_add_f32_e32 v159, 1.0, v159
	v_rcp_f32_e32 v184, v159
	v_fma_f32 v159, v103, v166, v39
	v_mul_f32_e32 v159, 0xbfb8aa3b, v159
	v_exp_f32_e32 v159, v159
	s_nop 0
	v_add_f32_e32 v159, 1.0, v159
	v_rcp_f32_e32 v185, v159
	v_fma_f32 v159, v96, v166, v32
	v_mul_f32_e32 v159, 0xbfb8aa3b, v159
	v_exp_f32_e32 v159, v159
	v_pk_mul_f32 v[184:185], v[188:189], v[184:185]
	flat_store_dwordx4 v[164:165], v[182:185]
	v_add_f32_e32 v159, 1.0, v159
	s_nop 0
	v_rcp_f32_e32 v182, v159
	v_fma_f32 v159, v97, v166, v33
	v_mul_f32_e32 v159, 0xbfb8aa3b, v159
	v_exp_f32_e32 v159, v159
	s_nop 0
	v_add_f32_e32 v159, 1.0, v159
	v_rcp_f32_e32 v183, v159
	v_fma_f32 v159, v98, v166, v34
	v_mul_f32_e32 v159, 0xbfb8aa3b, v159
	v_exp_f32_e32 v159, v159
	v_pk_mul_f32 v[182:183], v[186:187], v[182:183]
	v_add_f32_e32 v159, 1.0, v159
	v_rcp_f32_e32 v184, v159
	v_fma_f32 v159, v99, v166, v35
	v_mul_f32_e32 v159, 0xbfb8aa3b, v159
	v_exp_f32_e32 v159, v159
	v_pk_fma_f32 v[166:167], v[106:107], v[166:167], v[50:51] op_sel_hi:[1,0,1]
	v_add_f32_e32 v159, 1.0, v159
	v_rcp_f32_e32 v185, v159
	s_nop 0
	v_pk_mul_f32 v[184:185], v[166:167], v[184:185]
	flat_store_dwordx4 v[164:165], v[182:185] offset:16
	s_nop 1
	v_or_b32_e32 v164, 48, v158
	v_ashrrev_i32_e32 v165, 31, v164
	v_lshlrev_b64 v[164:165], 10, v[164:165]
	v_lshl_add_u64 v[164:165], s[16:17], 0, v[164:165]
	v_lshl_add_u64 v[164:165], v[164:165], 0, v[162:163]
	v_fmamk_f32 v159, v216, 0x3a800000, v224
	v_cmp_gt_f32_e32 vcc, s33, v159
	v_mul_f32_e32 v166, 0x4b800000, v159
	s_nop 0
	v_cndmask_b32_e32 v159, v159, v166, vcc
	v_rsq_f32_e32 v159, v159
	s_nop 0
	v_mul_f32_e32 v166, 0x45800000, v159
	v_cndmask_b32_e32 v166, v159, v166, vcc
	v_fma_f32 v159, v84, v166, v36
	v_mul_f32_e32 v159, 0xbfb8aa3b, v159
	v_exp_f32_e32 v159, v159
	v_pk_fma_f32 v[186:187], v[92:93], v[166:167], v[52:53] op_sel_hi:[1,0,1]
	v_pk_fma_f32 v[188:189], v[94:95], v[166:167], v[54:55] op_sel_hi:[1,0,1]
	v_add_f32_e32 v159, 1.0, v159
	v_rcp_f32_e32 v182, v159
	v_fma_f32 v159, v85, v166, v37
	v_mul_f32_e32 v159, 0xbfb8aa3b, v159
	v_exp_f32_e32 v159, v159
	s_nop 0
	v_add_f32_e32 v159, 1.0, v159
	v_rcp_f32_e32 v183, v159
	v_fma_f32 v159, v86, v166, v38
	v_mul_f32_e32 v159, 0xbfb8aa3b, v159
	v_exp_f32_e32 v159, v159
	v_pk_mul_f32 v[182:183], v[186:187], v[182:183]
	v_pk_fma_f32 v[186:187], v[88:89], v[166:167], v[48:49] op_sel_hi:[1,0,1]
	v_add_f32_e32 v159, 1.0, v159
	v_rcp_f32_e32 v184, v159
	v_fma_f32 v159, v87, v166, v39
	v_mul_f32_e32 v159, 0xbfb8aa3b, v159
	v_exp_f32_e32 v159, v159
	s_nop 0
	v_add_f32_e32 v159, 1.0, v159
	v_rcp_f32_e32 v185, v159
	v_fma_f32 v159, v80, v166, v32
	v_mul_f32_e32 v159, 0xbfb8aa3b, v159
	v_exp_f32_e32 v159, v159
	v_pk_mul_f32 v[184:185], v[188:189], v[184:185]
	flat_store_dwordx4 v[164:165], v[182:185]
	v_add_f32_e32 v159, 1.0, v159
	s_nop 0
	v_rcp_f32_e32 v182, v159
	v_fma_f32 v159, v81, v166, v33
	v_mul_f32_e32 v159, 0xbfb8aa3b, v159
	v_exp_f32_e32 v159, v159
	s_nop 0
	v_add_f32_e32 v159, 1.0, v159
	v_rcp_f32_e32 v183, v159
	v_fma_f32 v159, v82, v166, v34
	v_mul_f32_e32 v159, 0xbfb8aa3b, v159
	v_exp_f32_e32 v159, v159
	v_pk_mul_f32 v[182:183], v[186:187], v[182:183]
	v_add_f32_e32 v159, 1.0, v159
	v_rcp_f32_e32 v184, v159
	v_fma_f32 v159, v83, v166, v35
	v_mul_f32_e32 v159, 0xbfb8aa3b, v159
	v_exp_f32_e32 v159, v159
	v_pk_fma_f32 v[166:167], v[90:91], v[166:167], v[50:51] op_sel_hi:[1,0,1]
	v_add_f32_e32 v159, 1.0, v159
	v_rcp_f32_e32 v185, v159
	s_nop 0
	v_pk_mul_f32 v[184:185], v[166:167], v[184:185]
	flat_store_dwordx4 v[164:165], v[182:185] offset:16
	s_nop 1
	v_add_u32_e32 v164, 0x80, v158
	v_ashrrev_i32_e32 v165, 31, v164
	v_lshlrev_b64 v[164:165], 10, v[164:165]
	v_lshl_add_u64 v[164:165], s[16:17], 0, v[164:165]
	v_lshl_add_u64 v[164:165], v[164:165], 0, v[162:163]
	v_fmamk_f32 v159, v217, 0x3a800000, v224
	v_cmp_gt_f32_e32 vcc, s33, v159
	v_mul_f32_e32 v166, 0x4b800000, v159
	s_nop 0
	v_cndmask_b32_e32 v159, v159, v166, vcc
	v_rsq_f32_e32 v159, v159
	s_nop 0
	v_mul_f32_e32 v166, 0x45800000, v159
	v_cndmask_b32_e32 v166, v159, v166, vcc
	v_fma_f32 v159, v68, v166, v36
	v_mul_f32_e32 v159, 0xbfb8aa3b, v159
	v_exp_f32_e32 v159, v159
	v_pk_fma_f32 v[186:187], v[76:77], v[166:167], v[52:53] op_sel_hi:[1,0,1]
; __device__ __forceinline__ float sigm(float v) { return __builtin_amdgcn_rcpf(1.f + __builtin_amdgcn_exp2f(-1.4426950408889634f * v)); }
;     __device__ __forceinline__ void operator()(const f32x4 (&acc)[2][2][4][2], const Unit& u, int wr, int wc, int fr, int fq) const {
;     ...
;             const int ch0 = 128 * (pn - 7) + 32 * wc + 8 * fq;
; #pragma unroll
;             for (int ai = 0; ai < 2; ++ai)
; #pragma unroll
;                 for (int m = 0; m < 4; ++m) {
;                     const int row = pm * 256 + ai * 128 + wr * 64 + m * 16 + fr;
;                     const float rinv = rsqrtf(rowsq[row] * (1.f / DM) + EPSN);
; #pragma unroll
;                     for (int n = 0; n < 2; ++n) {
;                         const f32x4 a = acc[ai][0][m][n] * rinv + bv[0][n], g = acc[ai][1][m][n] * rinv + bv[1][n];
;                         f32x4 o;
; #pragma unroll
;                         for (int j = 0; j < 4; ++j) o[j] = a[j] * sigm(g[j]);
;                         *(f32x4*)(uconv + (size_t)row * 256 + ch0 + 4 * n) = o;
;                     }
	v_pk_fma_f32 v[188:189], v[78:79], v[166:167], v[54:55] op_sel_hi:[1,0,1]
	v_add_f32_e32 v159, 1.0, v159
	v_rcp_f32_e32 v182, v159
	v_fma_f32 v159, v69, v166, v37
	v_mul_f32_e32 v159, 0xbfb8aa3b, v159
	v_exp_f32_e32 v159, v159
	s_nop 0
	v_add_f32_e32 v159, 1.0, v159
	v_rcp_f32_e32 v183, v159
	v_fma_f32 v159, v70, v166, v38
	v_mul_f32_e32 v159, 0xbfb8aa3b, v159
	v_exp_f32_e32 v159, v159
	v_pk_mul_f32 v[182:183], v[186:187], v[182:183]
	v_pk_fma_f32 v[186:187], v[72:73], v[166:167], v[48:49] op_sel_hi:[1,0,1]
	v_add_f32_e32 v159, 1.0, v159
	v_rcp_f32_e32 v184, v159
	v_fma_f32 v159, v71, v166, v39
	v_mul_f32_e32 v159, 0xbfb8aa3b, v159
	v_exp_f32_e32 v159, v159
	s_nop 0
	v_add_f32_e32 v159, 1.0, v159
	v_rcp_f32_e32 v185, v159
	v_fma_f32 v159, v64, v166, v32
	v_mul_f32_e32 v159, 0xbfb8aa3b, v159
	v_exp_f32_e32 v159, v159
	v_pk_mul_f32 v[184:185], v[188:189], v[184:185]
	flat_store_dwordx4 v[164:165], v[182:185]
	v_add_f32_e32 v159, 1.0, v159
	s_nop 0
	v_rcp_f32_e32 v182, v159
	v_fma_f32 v159, v65, v166, v33
	v_mul_f32_e32 v159, 0xbfb8aa3b, v159
	v_exp_f32_e32 v159, v159
	s_nop 0
	v_add_f32_e32 v159, 1.0, v159
	v_rcp_f32_e32 v183, v159
	v_fma_f32 v159, v66, v166, v34
	v_mul_f32_e32 v159, 0xbfb8aa3b, v159
	v_exp_f32_e32 v159, v159
	v_pk_mul_f32 v[182:183], v[186:187], v[182:183]
	v_add_f32_e32 v159, 1.0, v159
	v_rcp_f32_e32 v184, v159
	v_fma_f32 v159, v67, v166, v35
	v_mul_f32_e32 v159, 0xbfb8aa3b, v159
	v_exp_f32_e32 v159, v159
	v_pk_fma_f32 v[166:167], v[74:75], v[166:167], v[50:51] op_sel_hi:[1,0,1]
	v_add_f32_e32 v159, 1.0, v159
	v_rcp_f32_e32 v185, v159
	s_nop 0
	v_pk_mul_f32 v[184:185], v[166:167], v[184:185]
	flat_store_dwordx4 v[164:165], v[182:185] offset:16
	s_nop 1
	v_add_u32_e32 v164, 0x90, v158
	v_ashrrev_i32_e32 v165, 31, v164
	v_lshlrev_b64 v[164:165], 10, v[164:165]
	v_lshl_add_u64 v[164:165], s[16:17], 0, v[164:165]
	v_lshl_add_u64 v[164:165], v[164:165], 0, v[162:163]
	v_fmamk_f32 v159, v218, 0x3a800000, v224
	v_cmp_gt_f32_e32 vcc, s33, v159
	v_mul_f32_e32 v166, 0x4b800000, v159
	s_nop 0
	v_cndmask_b32_e32 v159, v159, v166, vcc
	v_rsq_f32_e32 v159, v159
	s_nop 0
	v_mul_f32_e32 v166, 0x45800000, v159
	v_cndmask_b32_e32 v166, v159, v166, vcc
	v_fma_f32 v159, v44, v166, v36
	v_mul_f32_e32 v159, 0xbfb8aa3b, v159
	v_exp_f32_e32 v159, v159
	v_pk_fma_f32 v[186:187], v[60:61], v[166:167], v[52:53] op_sel_hi:[1,0,1]
	v_pk_fma_f32 v[188:189], v[62:63], v[166:167], v[54:55] op_sel_hi:[1,0,1]
	v_add_f32_e32 v159, 1.0, v159
	v_rcp_f32_e32 v182, v159
	v_fma_f32 v159, v45, v166, v37
	v_mul_f32_e32 v159, 0xbfb8aa3b, v159
	v_exp_f32_e32 v159, v159
	s_nop 0
	v_add_f32_e32 v159, 1.0, v159
	v_rcp_f32_e32 v183, v159
	v_fma_f32 v159, v46, v166, v38
	v_mul_f32_e32 v159, 0xbfb8aa3b, v159
	v_exp_f32_e32 v159, v159
	v_pk_mul_f32 v[182:183], v[186:187], v[182:183]
	v_pk_fma_f32 v[186:187], v[56:57], v[166:167], v[48:49] op_sel_hi:[1,0,1]
	v_add_f32_e32 v159, 1.0, v159
	v_rcp_f32_e32 v184, v159
	v_fma_f32 v159, v47, v166, v39
	v_mul_f32_e32 v159, 0xbfb8aa3b, v159
	v_exp_f32_e32 v159, v159
	s_nop 0
	v_add_f32_e32 v159, 1.0, v159
	v_rcp_f32_e32 v185, v159
	v_fma_f32 v159, v40, v166, v32
	v_mul_f32_e32 v159, 0xbfb8aa3b, v159
	v_exp_f32_e32 v159, v159
	v_pk_mul_f32 v[184:185], v[188:189], v[184:185]
	flat_store_dwordx4 v[164:165], v[182:185]
	v_add_f32_e32 v159, 1.0, v159
	s_nop 0
	v_rcp_f32_e32 v182, v159
	v_fma_f32 v159, v41, v166, v33
	v_mul_f32_e32 v159, 0xbfb8aa3b, v159
	v_exp_f32_e32 v159, v159
	s_nop 0
	v_add_f32_e32 v159, 1.0, v159
	v_rcp_f32_e32 v183, v159
	v_fma_f32 v159, v42, v166, v34
	v_mul_f32_e32 v159, 0xbfb8aa3b, v159
	v_exp_f32_e32 v159, v159
	v_pk_mul_f32 v[182:183], v[186:187], v[182:183]
	v_add_f32_e32 v159, 1.0, v159
	v_rcp_f32_e32 v184, v159
	v_fma_f32 v159, v43, v166, v35
	v_mul_f32_e32 v159, 0xbfb8aa3b, v159
	v_exp_f32_e32 v159, v159
	v_pk_fma_f32 v[166:167], v[58:59], v[166:167], v[50:51] op_sel_hi:[1,0,1]
	v_add_f32_e32 v159, 1.0, v159
	v_rcp_f32_e32 v185, v159
	s_nop 0
	v_pk_mul_f32 v[184:185], v[166:167], v[184:185]
	flat_store_dwordx4 v[164:165], v[182:185] offset:16
	s_nop 1
	v_add_u32_e32 v164, 0xa0, v158
	v_ashrrev_i32_e32 v165, 31, v164
	v_lshlrev_b64 v[164:165], 10, v[164:165]
	v_lshl_add_u64 v[164:165], s[16:17], 0, v[164:165]
	v_lshl_add_u64 v[164:165], v[164:165], 0, v[162:163]
	v_fmamk_f32 v159, v219, 0x3a800000, v224
	v_cmp_gt_f32_e32 vcc, s33, v159
	v_mul_f32_e32 v166, 0x4b800000, v159
	s_nop 0
	v_cndmask_b32_e32 v159, v159, v166, vcc
	v_rsq_f32_e32 v159, v159
	s_nop 0
	v_mul_f32_e32 v166, 0x45800000, v159
	v_cndmask_b32_e32 v166, v159, v166, vcc
	v_fma_f32 v159, v20, v166, v36
	v_mul_f32_e32 v159, 0xbfb8aa3b, v159
	v_exp_f32_e32 v159, v159
	v_pk_fma_f32 v[186:187], v[28:29], v[166:167], v[52:53] op_sel_hi:[1,0,1]
	v_pk_fma_f32 v[188:189], v[30:31], v[166:167], v[54:55] op_sel_hi:[1,0,1]
	v_add_f32_e32 v159, 1.0, v159
	v_rcp_f32_e32 v182, v159
	v_fma_f32 v159, v21, v166, v37
	v_mul_f32_e32 v159, 0xbfb8aa3b, v159
	v_exp_f32_e32 v159, v159
	s_nop 0
	v_add_f32_e32 v159, 1.0, v159
	v_rcp_f32_e32 v183, v159
	v_fma_f32 v159, v22, v166, v38
	v_mul_f32_e32 v159, 0xbfb8aa3b, v159
	v_exp_f32_e32 v159, v159
	v_pk_mul_f32 v[182:183], v[186:187], v[182:183]
	v_pk_fma_f32 v[186:187], v[24:25], v[166:167], v[48:49] op_sel_hi:[1,0,1]
	v_add_f32_e32 v159, 1.0, v159
	v_rcp_f32_e32 v184, v159
	v_fma_f32 v159, v23, v166, v39
	v_mul_f32_e32 v159, 0xbfb8aa3b, v159
	v_exp_f32_e32 v159, v159
	s_nop 0
	v_add_f32_e32 v159, 1.0, v159
	v_rcp_f32_e32 v185, v159
	v_fma_f32 v159, v16, v166, v32
	v_mul_f32_e32 v159, 0xbfb8aa3b, v159
	v_exp_f32_e32 v159, v159
	v_pk_mul_f32 v[184:185], v[188:189], v[184:185]
	flat_store_dwordx4 v[164:165], v[182:185]
; __device__ __forceinline__ float sigm(float v) { return __builtin_amdgcn_rcpf(1.f + __builtin_amdgcn_exp2f(-1.4426950408889634f * v)); }
;     __device__ __forceinline__ void operator()(const f32x4 (&acc)[2][2][4][2], const Unit& u, int wr, int wc, int fr, int fq) const {
;     ...
;         } else if (pn == 6) {
; #pragma unroll
;             for (int ai = 0; ai < 2; ++ai)
; #pragma unroll
;                 for (int m = 0; m < 4; ++m) {
;                     const int row = pm * 256 + ai * 128 + wr * 64 + m * 16 + fr;
;                     const float rinv = rsqrtf(rowsq[row] * (1.f / DM) + EPSN);
; #pragma unroll
;                     for (int bj = 0; bj < 2; ++bj)
; #pragma unroll
;                         for (int n = 0; n < 2; ++n) *(f32x4*)(upool + (size_t)row * 256 + 128 * bj + 32 * wc + 8 * fq + 4 * n) = acc[ai][bj][m][n] * rinv + bv[bj][n];
;                 }
;     ...
;             const int ch0 = 128 * (pn - 7) + 32 * wc + 8 * fq;
; #pragma unroll
;             for (int ai = 0; ai < 2; ++ai)
; #pragma unroll
;                 for (int m = 0; m < 4; ++m) {
;                     const int row = pm * 256 + ai * 128 + wr * 64 + m * 16 + fr;
;                     const float rinv = rsqrtf(rowsq[row] * (1.f / DM) + EPSN);
; #pragma unroll
;                     for (int n = 0; n < 2; ++n) {
;                         const f32x4 a = acc[ai][0][m][n] * rinv + bv[0][n], g = acc[ai][1][m][n] * rinv + bv[1][n];
;                         f32x4 o;
; #pragma unroll
;                         for (int j = 0; j < 4; ++j) o[j] = a[j] * sigm(g[j]);
;                         *(f32x4*)(uconv + (size_t)row * 256 + ch0 + 4 * n) = o;
;                     }
	v_add_f32_e32 v159, 1.0, v159
	s_nop 0
	v_rcp_f32_e32 v182, v159
	v_fma_f32 v159, v17, v166, v33
	v_mul_f32_e32 v159, 0xbfb8aa3b, v159
	v_exp_f32_e32 v159, v159
	s_nop 0
	v_add_f32_e32 v159, 1.0, v159
	v_rcp_f32_e32 v183, v159
	v_fma_f32 v159, v18, v166, v34
	v_mul_f32_e32 v159, 0xbfb8aa3b, v159
	v_exp_f32_e32 v159, v159
	v_pk_mul_f32 v[182:183], v[186:187], v[182:183]
	v_add_f32_e32 v159, 1.0, v159
	v_rcp_f32_e32 v184, v159
	v_fma_f32 v159, v19, v166, v35
	v_mul_f32_e32 v159, 0xbfb8aa3b, v159
	v_exp_f32_e32 v159, v159
	v_pk_fma_f32 v[166:167], v[26:27], v[166:167], v[50:51] op_sel_hi:[1,0,1]
	v_add_f32_e32 v159, 1.0, v159
	v_rcp_f32_e32 v185, v159
	s_nop 0
	v_pk_mul_f32 v[184:185], v[166:167], v[184:185]
	flat_store_dwordx4 v[164:165], v[182:185] offset:16
	s_nop 1
	v_add_u32_e32 v166, 0xb0, v158
	v_ashrrev_i32_e32 v167, 31, v166
	v_fmamk_f32 v159, v220, 0x3a800000, v224
	v_cmp_gt_f32_e32 vcc, s33, v159
	v_mul_f32_e32 v160, 0x4b800000, v159
	s_nop 0
	v_cndmask_b32_e32 v159, v159, v160, vcc
	v_rsq_f32_e32 v159, v159
	s_nop 0
	v_mul_f32_e32 v160, 0x45800000, v159
	v_cndmask_b32_e32 v164, v159, v160, vcc
	v_fma_f32 v159, v4, v164, v36
	v_mul_f32_e32 v159, 0xbfb8aa3b, v159
	v_exp_f32_e32 v159, v159
	v_lshlrev_b64 v[160:161], 10, v[166:167]
	v_lshl_add_u64 v[160:161], s[16:17], 0, v[160:161]
	v_lshl_add_u64 v[160:161], v[160:161], 0, v[162:163]
	v_add_f32_e32 v159, 1.0, v159
	v_rcp_f32_e32 v166, v159
	v_fma_f32 v159, v5, v164, v37
	v_mul_f32_e32 v159, 0xbfb8aa3b, v159
	v_exp_f32_e32 v159, v159
	v_pk_fma_f32 v[186:187], v[12:13], v[164:165], v[52:53] op_sel_hi:[1,0,1]
	v_pk_fma_f32 v[184:185], v[14:15], v[164:165], v[54:55] op_sel_hi:[1,0,1]
	v_add_f32_e32 v159, 1.0, v159
	v_rcp_f32_e32 v167, v159
	v_fma_f32 v159, v6, v164, v38
	v_mul_f32_e32 v159, 0xbfb8aa3b, v159
	v_exp_f32_e32 v159, v159
	s_nop 0
	v_add_f32_e32 v159, 1.0, v159
	v_rcp_f32_e32 v182, v159
	v_fma_f32 v159, v7, v164, v39
	v_mul_f32_e32 v159, 0xbfb8aa3b, v159
	v_exp_f32_e32 v159, v159
	s_nop 0
	v_add_f32_e32 v159, 1.0, v159
	v_rcp_f32_e32 v183, v159
	v_fma_f32 v159, v0, v164, v32
	v_mul_f32_e32 v159, 0xbfb8aa3b, v159
	v_exp_f32_e32 v159, v159
	v_pk_mul_f32 v[184:185], v[184:185], v[182:183]
	v_pk_mul_f32 v[182:183], v[186:187], v[166:167]
	flat_store_dwordx4 v[160:161], v[182:185]
	v_add_f32_e32 v159, 1.0, v159
	v_rcp_f32_e32 v162, v159
	v_fma_f32 v159, v1, v164, v33
	v_mul_f32_e32 v159, 0xbfb8aa3b, v159
	v_exp_f32_e32 v159, v159
	v_pk_fma_f32 v[182:183], v[8:9], v[164:165], v[48:49] op_sel_hi:[1,0,1]
	v_add_f32_e32 v159, 1.0, v159
	v_rcp_f32_e32 v163, v159
	v_fma_f32 v159, v2, v164, v34
	v_mul_f32_e32 v159, 0xbfb8aa3b, v159
	v_exp_f32_e32 v159, v159
	v_pk_mul_f32 v[162:163], v[182:183], v[162:163]
	v_add_f32_e32 v159, 1.0, v159
	v_rcp_f32_e32 v166, v159
	v_fma_f32 v159, v3, v164, v35
	v_mul_f32_e32 v159, 0xbfb8aa3b, v159
	v_exp_f32_e32 v159, v159
	v_pk_fma_f32 v[164:165], v[10:11], v[164:165], v[50:51] op_sel_hi:[1,0,1]
	v_add_f32_e32 v159, 1.0, v159
	v_rcp_f32_e32 v167, v159
	s_nop 0
	v_pk_mul_f32 v[164:165], v[164:165], v[166:167]
	flat_store_dwordx4 v[160:161], v[162:165] offset:16
.LBB0_322:
	s_andn2_b64 vcc, exec, s[0:1]
	s_cbranch_vccnz .LBB0_324
	v_ashrrev_i32_e32 v159, 31, v158
	v_lshl_add_u64 v[160:161], v[158:159], 2, s[12:13]
	flat_load_dword v162, v[160:161]
	flat_load_dword v214, v[160:161] offset:64
	flat_load_dword v215, v[160:161] offset:128
	flat_load_dword v216, v[160:161] offset:192
	flat_load_dword v217, v[160:161] offset:512
	flat_load_dword v218, v[160:161] offset:576
	flat_load_dword v219, v[160:161] offset:640
	v_lshlrev_b64 v[182:183], 10, v[158:159]
	v_lshl_add_u64 v[182:183], v[152:153], 0, v[182:183]
	s_waitcnt vmcnt(0) lgkmcnt(0)
	v_fmamk_f32 v162, v162, 0x3a800000, v224
	v_cmp_gt_f32_e32 vcc, s33, v162
	v_mul_f32_e32 v163, 0x4b800000, v162
	s_nop 0
	v_cndmask_b32_e32 v162, v162, v163, vcc
	v_rsq_f32_e32 v162, v162
	s_nop 0
	v_mul_f32_e32 v163, 0x45800000, v162
	v_cndmask_b32_e32 v166, v162, v163, vcc
	v_pk_fma_f32 v[164:165], v[142:143], v[166:167], v[54:55] op_sel_hi:[1,0,1]
	v_pk_fma_f32 v[162:163], v[140:141], v[166:167], v[52:53] op_sel_hi:[1,0,1]
	flat_store_dwordx4 v[182:183], v[162:165]
	s_nop 1
	v_pk_fma_f32 v[164:165], v[138:139], v[166:167], v[50:51] op_sel_hi:[1,0,1]
	v_pk_fma_f32 v[162:163], v[136:137], v[166:167], v[48:49] op_sel_hi:[1,0,1]
	flat_store_dwordx4 v[182:183], v[162:165] offset:16
	s_nop 1
	v_pk_fma_f32 v[164:165], v[134:135], v[166:167], v[38:39] op_sel_hi:[1,0,1]
	v_pk_fma_f32 v[162:163], v[132:133], v[166:167], v[36:37] op_sel_hi:[1,0,1]
	flat_store_dwordx4 v[182:183], v[162:165] offset:512
	s_nop 1
	v_pk_fma_f32 v[164:165], v[130:131], v[166:167], v[34:35] op_sel_hi:[1,0,1]
	v_pk_fma_f32 v[162:163], v[128:129], v[166:167], v[32:33] op_sel_hi:[1,0,1]
	flat_store_dwordx4 v[182:183], v[162:165] offset:528
	s_nop 1
	v_fmamk_f32 v159, v214, 0x3a800000, v224
	v_cmp_gt_f32_e32 vcc, s33, v159
	v_mul_f32_e32 v164, 0x4b800000, v159
	v_or_b32_e32 v162, 16, v158
	v_cndmask_b32_e32 v159, v159, v164, vcc
	v_rsq_f32_e32 v159, v159
	v_ashrrev_i32_e32 v163, 31, v162
	v_lshlrev_b64 v[182:183], 10, v[162:163]
	v_lshl_add_u64 v[182:183], v[152:153], 0, v[182:183]
	v_mul_f32_e32 v164, 0x45800000, v159
	v_cndmask_b32_e32 v166, v159, v164, vcc
	v_pk_fma_f32 v[164:165], v[126:127], v[166:167], v[54:55] op_sel_hi:[1,0,1]
	v_pk_fma_f32 v[162:163], v[124:125], v[166:167], v[52:53] op_sel_hi:[1,0,1]
	flat_store_dwordx4 v[182:183], v[162:165]
	s_nop 1
	v_pk_fma_f32 v[164:165], v[122:123], v[166:167], v[50:51] op_sel_hi:[1,0,1]
	v_pk_fma_f32 v[162:163], v[120:121], v[166:167], v[48:49] op_sel_hi:[1,0,1]
	flat_store_dwordx4 v[182:183], v[162:165] offset:16
;     __device__ __forceinline__ void operator()(const f32x4 (&acc)[2][2][4][2], const Unit& u, int wr, int wc, int fr, int fq) const {
;     ...
;         } else if (pn == 6) {
; #pragma unroll
;             for (int ai = 0; ai < 2; ++ai)
; #pragma unroll
;                 for (int m = 0; m < 4; ++m) {
;                     const int row = pm * 256 + ai * 128 + wr * 64 + m * 16 + fr;
;                     const float rinv = rsqrtf(rowsq[row] * (1.f / DM) + EPSN);
; #pragma unroll
;                     for (int bj = 0; bj < 2; ++bj)
; #pragma unroll
;                         for (int n = 0; n < 2; ++n) *(f32x4*)(upool + (size_t)row * 256 + 128 * bj + 32 * wc + 8 * fq + 4 * n) = acc[ai][bj][m][n] * rinv + bv[bj][n];
;                 }
	s_nop 1
	v_pk_fma_f32 v[164:165], v[118:119], v[166:167], v[38:39] op_sel_hi:[1,0,1]
	v_pk_fma_f32 v[162:163], v[116:117], v[166:167], v[36:37] op_sel_hi:[1,0,1]
	flat_store_dwordx4 v[182:183], v[162:165] offset:512
	s_nop 1
	v_pk_fma_f32 v[164:165], v[114:115], v[166:167], v[34:35] op_sel_hi:[1,0,1]
	v_pk_fma_f32 v[162:163], v[112:113], v[166:167], v[32:33] op_sel_hi:[1,0,1]
	flat_store_dwordx4 v[182:183], v[162:165] offset:528
	s_nop 1
	v_fmamk_f32 v159, v215, 0x3a800000, v224
	v_cmp_gt_f32_e32 vcc, s33, v159
	v_mul_f32_e32 v164, 0x4b800000, v159
	v_or_b32_e32 v162, 32, v158
	v_cndmask_b32_e32 v159, v159, v164, vcc
	v_rsq_f32_e32 v159, v159
	v_ashrrev_i32_e32 v163, 31, v162
	v_lshlrev_b64 v[182:183], 10, v[162:163]
	v_lshl_add_u64 v[182:183], v[152:153], 0, v[182:183]
	v_mul_f32_e32 v164, 0x45800000, v159
	v_cndmask_b32_e32 v166, v159, v164, vcc
	v_pk_fma_f32 v[164:165], v[110:111], v[166:167], v[54:55] op_sel_hi:[1,0,1]
	v_pk_fma_f32 v[162:163], v[108:109], v[166:167], v[52:53] op_sel_hi:[1,0,1]
	flat_store_dwordx4 v[182:183], v[162:165]
	s_nop 1
	v_pk_fma_f32 v[164:165], v[106:107], v[166:167], v[50:51] op_sel_hi:[1,0,1]
	v_pk_fma_f32 v[162:163], v[104:105], v[166:167], v[48:49] op_sel_hi:[1,0,1]
	flat_store_dwordx4 v[182:183], v[162:165] offset:16
	s_nop 1
	v_pk_fma_f32 v[164:165], v[102:103], v[166:167], v[38:39] op_sel_hi:[1,0,1]
	v_pk_fma_f32 v[162:163], v[100:101], v[166:167], v[36:37] op_sel_hi:[1,0,1]
	flat_store_dwordx4 v[182:183], v[162:165] offset:512
	s_nop 1
	v_pk_fma_f32 v[164:165], v[98:99], v[166:167], v[34:35] op_sel_hi:[1,0,1]
	v_pk_fma_f32 v[162:163], v[96:97], v[166:167], v[32:33] op_sel_hi:[1,0,1]
	flat_store_dwordx4 v[182:183], v[162:165] offset:528
	s_nop 1
	v_fmamk_f32 v159, v216, 0x3a800000, v224
	v_cmp_gt_f32_e32 vcc, s33, v159
	v_mul_f32_e32 v164, 0x4b800000, v159
	v_or_b32_e32 v162, 48, v158
	v_cndmask_b32_e32 v159, v159, v164, vcc
	v_rsq_f32_e32 v159, v159
	v_ashrrev_i32_e32 v163, 31, v162
	v_lshlrev_b64 v[182:183], 10, v[162:163]
	v_lshl_add_u64 v[182:183], v[152:153], 0, v[182:183]
	v_mul_f32_e32 v164, 0x45800000, v159
	v_cndmask_b32_e32 v166, v159, v164, vcc
	v_pk_fma_f32 v[164:165], v[94:95], v[166:167], v[54:55] op_sel_hi:[1,0,1]
	v_pk_fma_f32 v[162:163], v[92:93], v[166:167], v[52:53] op_sel_hi:[1,0,1]
	flat_store_dwordx4 v[182:183], v[162:165]
	s_nop 1
	v_pk_fma_f32 v[164:165], v[90:91], v[166:167], v[50:51] op_sel_hi:[1,0,1]
	v_pk_fma_f32 v[162:163], v[88:89], v[166:167], v[48:49] op_sel_hi:[1,0,1]
	flat_store_dwordx4 v[182:183], v[162:165] offset:16
	s_nop 1
	v_pk_fma_f32 v[164:165], v[86:87], v[166:167], v[38:39] op_sel_hi:[1,0,1]
	v_pk_fma_f32 v[162:163], v[84:85], v[166:167], v[36:37] op_sel_hi:[1,0,1]
	flat_store_dwordx4 v[182:183], v[162:165] offset:512
	s_nop 1
	v_pk_fma_f32 v[164:165], v[82:83], v[166:167], v[34:35] op_sel_hi:[1,0,1]
	v_pk_fma_f32 v[162:163], v[80:81], v[166:167], v[32:33] op_sel_hi:[1,0,1]
	flat_store_dwordx4 v[182:183], v[162:165] offset:528
	s_nop 1
	v_fmamk_f32 v159, v217, 0x3a800000, v224
	v_cmp_gt_f32_e32 vcc, s33, v159
	v_mul_f32_e32 v164, 0x4b800000, v159
	v_add_u32_e32 v162, 0x80, v158
	v_cndmask_b32_e32 v159, v159, v164, vcc
	v_rsq_f32_e32 v159, v159
	v_ashrrev_i32_e32 v163, 31, v162
	v_lshlrev_b64 v[182:183], 10, v[162:163]
	v_lshl_add_u64 v[182:183], v[152:153], 0, v[182:183]
	v_mul_f32_e32 v164, 0x45800000, v159
	v_cndmask_b32_e32 v166, v159, v164, vcc
	v_pk_fma_f32 v[164:165], v[78:79], v[166:167], v[54:55] op_sel_hi:[1,0,1]
	v_pk_fma_f32 v[162:163], v[76:77], v[166:167], v[52:53] op_sel_hi:[1,0,1]
	flat_store_dwordx4 v[182:183], v[162:165]
	s_nop 1
	v_pk_fma_f32 v[164:165], v[74:75], v[166:167], v[50:51] op_sel_hi:[1,0,1]
	v_pk_fma_f32 v[162:163], v[72:73], v[166:167], v[48:49] op_sel_hi:[1,0,1]
	flat_store_dwordx4 v[182:183], v[162:165] offset:16
	s_nop 1
	v_pk_fma_f32 v[164:165], v[70:71], v[166:167], v[38:39] op_sel_hi:[1,0,1]
	v_pk_fma_f32 v[162:163], v[68:69], v[166:167], v[36:37] op_sel_hi:[1,0,1]
	flat_store_dwordx4 v[182:183], v[162:165] offset:512
	s_nop 1
	v_pk_fma_f32 v[164:165], v[66:67], v[166:167], v[34:35] op_sel_hi:[1,0,1]
	v_pk_fma_f32 v[162:163], v[64:65], v[166:167], v[32:33] op_sel_hi:[1,0,1]
	flat_store_dwordx4 v[182:183], v[162:165] offset:528
	s_nop 1
	v_fmamk_f32 v159, v218, 0x3a800000, v224
	v_cmp_gt_f32_e32 vcc, s33, v159
	v_mul_f32_e32 v164, 0x4b800000, v159
	v_add_u32_e32 v162, 0x90, v158
	v_cndmask_b32_e32 v159, v159, v164, vcc
	v_rsq_f32_e32 v159, v159
	v_ashrrev_i32_e32 v163, 31, v162
	v_lshlrev_b64 v[182:183], 10, v[162:163]
	v_lshl_add_u64 v[182:183], v[152:153], 0, v[182:183]
	v_mul_f32_e32 v164, 0x45800000, v159
	v_cndmask_b32_e32 v166, v159, v164, vcc
	v_pk_fma_f32 v[164:165], v[62:63], v[166:167], v[54:55] op_sel_hi:[1,0,1]
	v_pk_fma_f32 v[162:163], v[60:61], v[166:167], v[52:53] op_sel_hi:[1,0,1]
	flat_store_dwordx4 v[182:183], v[162:165]
	s_nop 1
	v_pk_fma_f32 v[164:165], v[58:59], v[166:167], v[50:51] op_sel_hi:[1,0,1]
	v_pk_fma_f32 v[162:163], v[56:57], v[166:167], v[48:49] op_sel_hi:[1,0,1]
	flat_store_dwordx4 v[182:183], v[162:165] offset:16
	s_nop 1
	v_pk_fma_f32 v[164:165], v[46:47], v[166:167], v[38:39] op_sel_hi:[1,0,1]
	v_pk_fma_f32 v[162:163], v[44:45], v[166:167], v[36:37] op_sel_hi:[1,0,1]
	flat_store_dwordx4 v[182:183], v[162:165] offset:512
	s_nop 1
	v_pk_fma_f32 v[164:165], v[42:43], v[166:167], v[34:35] op_sel_hi:[1,0,1]
	v_pk_fma_f32 v[162:163], v[40:41], v[166:167], v[32:33] op_sel_hi:[1,0,1]
	flat_store_dwordx4 v[182:183], v[162:165] offset:528
	s_nop 1
	v_fmamk_f32 v159, v219, 0x3a800000, v224
	v_cmp_gt_f32_e32 vcc, s33, v159
	v_mul_f32_e32 v164, 0x4b800000, v159
	v_add_u32_e32 v162, 0xa0, v158
	v_cndmask_b32_e32 v159, v159, v164, vcc
	v_rsq_f32_e32 v159, v159
	v_ashrrev_i32_e32 v163, 31, v162
	v_lshlrev_b64 v[182:183], 10, v[162:163]
	v_lshl_add_u64 v[182:183], v[152:153], 0, v[182:183]
	v_mul_f32_e32 v164, 0x45800000, v159
	v_cndmask_b32_e32 v166, v159, v164, vcc
	v_pk_fma_f32 v[164:165], v[30:31], v[166:167], v[54:55] op_sel_hi:[1,0,1]
	v_pk_fma_f32 v[162:163], v[28:29], v[166:167], v[52:53] op_sel_hi:[1,0,1]
	flat_store_dwordx4 v[182:183], v[162:165]
	v_add_u32_e32 v158, 0xb0, v158
	v_ashrrev_i32_e32 v159, 31, v158
	v_pk_fma_f32 v[164:165], v[26:27], v[166:167], v[50:51] op_sel_hi:[1,0,1]
	v_pk_fma_f32 v[162:163], v[24:25], v[166:167], v[48:49] op_sel_hi:[1,0,1]
	flat_store_dwordx4 v[182:183], v[162:165] offset:16
	s_nop 1
	v_pk_fma_f32 v[164:165], v[22:23], v[166:167], v[38:39] op_sel_hi:[1,0,1]
	v_pk_fma_f32 v[162:163], v[20:21], v[166:167], v[36:37] op_sel_hi:[1,0,1]
	flat_store_dwordx4 v[182:183], v[162:165] offset:512
	s_nop 1
	v_pk_fma_f32 v[164:165], v[18:19], v[166:167], v[34:35] op_sel_hi:[1,0,1]
	v_pk_fma_f32 v[162:163], v[16:17], v[166:167], v[32:33] op_sel_hi:[1,0,1]
	flat_store_dwordx4 v[182:183], v[162:165] offset:528
	flat_load_dword v160, v[160:161] offset:704
	s_waitcnt vmcnt(0) lgkmcnt(0)
;     __device__ __forceinline__ void operator()(const f32x4 (&acc)[2][2][4][2], const Unit& u, int wr, int wc, int fr, int fq) const {
;     ...
;         } else if (pn == 6) {
; #pragma unroll
;             for (int ai = 0; ai < 2; ++ai)
; #pragma unroll
;                 for (int m = 0; m < 4; ++m) {
;                     const int row = pm * 256 + ai * 128 + wr * 64 + m * 16 + fr;
;                     const float rinv = rsqrtf(rowsq[row] * (1.f / DM) + EPSN);
; #pragma unroll
;                     for (int bj = 0; bj < 2; ++bj)
; #pragma unroll
;                         for (int n = 0; n < 2; ++n) *(f32x4*)(upool + (size_t)row * 256 + 128 * bj + 32 * wc + 8 * fq + 4 * n) = acc[ai][bj][m][n] * rinv + bv[bj][n];
;                 }
	v_fmamk_f32 v160, v160, 0x3a800000, v224
	v_cmp_gt_f32_e32 vcc, s33, v160
	v_mul_f32_e32 v161, 0x4b800000, v160
	v_lshlrev_b64 v[164:165], 10, v[158:159]
	v_cndmask_b32_e32 v160, v160, v161, vcc
	v_rsq_f32_e32 v160, v160
	v_lshl_add_u64 v[164:165], v[152:153], 0, v[164:165]
	v_mul_f32_e32 v161, 0x45800000, v160
	v_cndmask_b32_e32 v162, v160, v161, vcc
	v_pk_fma_f32 v[160:161], v[14:15], v[162:163], v[54:55] op_sel_hi:[1,0,1]
	v_pk_fma_f32 v[158:159], v[12:13], v[162:163], v[52:53] op_sel_hi:[1,0,1]
	flat_store_dwordx4 v[164:165], v[158:161]
	s_nop 1
	v_pk_fma_f32 v[160:161], v[10:11], v[162:163], v[50:51] op_sel_hi:[1,0,1]
	v_pk_fma_f32 v[158:159], v[8:9], v[162:163], v[48:49] op_sel_hi:[1,0,1]
	flat_store_dwordx4 v[164:165], v[158:161] offset:16
	s_nop 1
	v_pk_fma_f32 v[160:161], v[6:7], v[162:163], v[38:39] op_sel_hi:[1,0,1]
	v_pk_fma_f32 v[158:159], v[4:5], v[162:163], v[36:37] op_sel_hi:[1,0,1]
	flat_store_dwordx4 v[164:165], v[158:161] offset:512
	s_nop 1
	v_pk_fma_f32 v[160:161], v[2:3], v[162:163], v[34:35] op_sel_hi:[1,0,1]
	v_pk_fma_f32 v[158:159], v[0:1], v[162:163], v[32:33] op_sel_hi:[1,0,1]
	flat_store_dwordx4 v[164:165], v[158:161] offset:528

; __device__ __forceinline__ unsigned pkbf(float lo, float hi) { return pg8::cvt_pk_bf16(lo, hi); }
;     __device__ __forceinline__ void operator()(const f32x4 (&acc)[2][2][4][2], const Unit& u, int wr, int wc, int fr, int fq) const {
;     ...
;         } else if (pn < 6) {
; #pragma unroll
;             for (int ai = 0; ai < 2; ++ai)
; #pragma unroll
;                 for (int m = 0; m < 4; ++m) {
;                     const int row = pm * 256 + ai * 128 + wr * 64 + m * 16 + fr;
;                     const float rinv = rsqrtf(rowsq[row] * (1.f / DM) + EPSN);
;                     int b, kidx;
;                     if (isctx) { const int rc = row - MLAT; b = rc >> 8; kidx = rc & 255; } else { b = row >> 13; kidx = CTXL + (row & (SEQ - 1)); }
; #pragma unroll
;                     for (int bj = 0; bj < 2; ++bj) {
;                         const f32x4 y0 = acc[ai][bj][m][0] * rinv + bv[bj][0], y1 = acc[ai][bj][m][1] * rinv + bv[bj][1];
;                         u32x4 w; w.x = pkbf(y0[0], y0[1]); w.y = pkbf(y0[2], y0[3]); w.z = pkbf(y1[0], y1[1]); w.w = pkbf(y1[2], y1[3]);
;                         const int head = 2 * (pn - 4) + bj;
;                         const size_t off = (size_t)(b * 4 + head) * (LK * 128) + (size_t)(kidx >> 6) * 8192 + (size_t)(voff(kidx & 63, 4 * wc + fq) >> 1);
;                         *(u32x4*)(Vb + off) = w;
;                     }
;                 }
.LBB0_327:
	s_lshl_b32 s0, s66, 8
	s_add_i32 s14, s0, s49
	v_or_b32_e32 v158, s14, v169
	v_ashrrev_i32_e32 v159, 31, v158
	v_lshl_add_u64 v[160:161], v[158:159], 2, s[12:13]
	flat_load_dword v159, v[160:161]
	s_add_i32 s0, s14, 0xffffc000
	s_ashr_i32 s30, s0, 8
	s_add_i32 s0, s14, 0xffffc080
	s_ashr_i32 s54, s0, 8
	s_lshl_b32 s21, s67, 1
	s_add_i32 s23, s14, 0x80
	s_add_i32 s21, s21, -8
	s_ashr_i32 s15, s14, 13
	s_ashr_i32 s31, s23, 13
	s_cmp_gt_i32 s66, 63
	s_cselect_b64 vcc, -1, 0
	v_bitop3_b32 v163, s14, v228, v169 bitop3:0xc8
	v_add_u32_e32 v163, 0x100, v163
	s_waitcnt vmcnt(0) lgkmcnt(0)
	v_fmamk_f32 v159, v159, 0x3a800000, v224
	v_cmp_gt_f32_e64 s[0:1], s33, v159
	v_mul_f32_e32 v162, 0x4b800000, v159
	s_nop 0
	v_cndmask_b32_e64 v159, v159, v162, s[0:1]
	v_rsq_f32_e32 v159, v159
	s_nop 0
	v_mul_f32_e32 v162, 0x45800000, v159
	v_cndmask_b32_e64 v162, v159, v162, s[0:1]
	v_bitop3_b32 v159, s14, v227, v169 bitop3:0xc8
	s_and_b64 s[0:1], vcc, exec
	s_cselect_b32 s0, s30, s15
	v_cndmask_b32_e32 v159, v163, v159, vcc
	s_cselect_b32 s54, s54, s31
	s_lshl_b32 s0, s0, 2
	v_lshrrev_b32_e32 v165, 2, v159
	s_add_i32 s0, s0, s21
	v_lshlrev_b32_e32 v163, 7, v159
	v_xor_b32_e32 v165, v165, v168
	v_and_b32_e32 v163, 0x400, v163
	v_lshlrev_b32_e32 v164, 5, v159
	v_lshlrev_b32_e32 v165, 3, v165
	s_mul_i32 s14, s0, 0x210000
	v_and_b32_e32 v165, 24, v165
	v_and_or_b32 v163, v164, s79, v163
	s_mul_hi_i32 s1, s0, 0x210000
	s_add_u32 s14, s45, s14
	v_or3_b32 v163, v163, v165, s64
	v_lshlrev_b32_e32 v159, 8, v159
	s_addc_u32 s15, s46, s1
	s_or_b32 s0, s0, 1
	v_and_b32_e32 v176, 0x3fc000, v159
	v_pk_fma_f32 v[142:143], v[142:143], v[162:163], v[54:55] op_sel_hi:[1,0,1]
	v_pk_fma_f32 v[140:141], v[140:141], v[162:163], v[52:53] op_sel_hi:[1,0,1]
	v_pk_fma_f32 v[136:137], v[136:137], v[162:163], v[48:49] op_sel_hi:[1,0,1]
	s_mul_hi_i32 s1, s0, 0x210000
	s_mul_i32 s0, s0, 0x210000
	v_pk_fma_f32 v[164:165], v[138:139], v[162:163], v[50:51] op_sel_hi:[1,0,1]
	v_cvt_pk_bf16_f32 v138, v140, v141
	v_cvt_pk_bf16_f32 v139, v142, v143
	v_cvt_pk_bf16_f32 v140, v136, v137
	v_lshl_add_u64 v[142:143], s[14:15], 0, v[176:177]
	v_lshlrev_b32_e32 v136, 1, v163
	v_mov_b32_e32 v137, v177
	s_add_u32 s30, s45, s0
	v_lshl_add_u64 v[142:143], v[142:143], 0, v[136:137]
	v_pk_fma_f32 v[132:133], v[132:133], v[162:163], v[36:37] op_sel_hi:[1,0,1]
	s_addc_u32 s31, s46, s1
	v_cvt_pk_bf16_f32 v141, v164, v165
	flat_store_dwordx4 v[142:143], v[138:141]
	v_pk_fma_f32 v[134:135], v[134:135], v[162:163], v[38:39] op_sel_hi:[1,0,1]
	s_nop 0
	v_pk_fma_f32 v[138:139], v[130:131], v[162:163], v[34:35] op_sel_hi:[1,0,1]
	v_pk_fma_f32 v[130:131], v[128:129], v[162:163], v[32:33] op_sel_hi:[1,0,1]
	v_cvt_pk_bf16_f32 v128, v132, v133
	v_lshl_add_u64 v[132:133], s[30:31], 0, v[176:177]
	v_lshl_add_u64 v[132:133], v[132:133], 0, v[136:137]
	v_cvt_pk_bf16_f32 v129, v134, v135
	v_cvt_pk_bf16_f32 v130, v130, v131
	v_cvt_pk_bf16_f32 v131, v138, v139
	flat_store_dwordx4 v[132:133], v[128:131]
	flat_load_dword v128, v[160:161] offset:64
	flat_load_dword v214, v[160:161] offset:128
	flat_load_dword v215, v[160:161] offset:192
	s_nop 0
	v_bitop3_b32 v130, v158, s84, 16 bitop3:0xc8
	v_add_u32_e32 v130, 0x100, v130
	s_waitcnt vmcnt(0) lgkmcnt(0)
	v_fmamk_f32 v128, v128, 0x3a800000, v224
	v_cmp_gt_f32_e64 s[0:1], s33, v128
	v_mul_f32_e32 v129, 0x4b800000, v128
	s_nop 0
	v_cndmask_b32_e64 v128, v128, v129, s[0:1]
	v_rsq_f32_e32 v128, v128
	s_nop 0
	v_mul_f32_e32 v129, 0x45800000, v128
	v_cndmask_b32_e64 v128, v128, v129, s[0:1]
	v_bitop3_b32 v129, v158, s95, 16 bitop3:0xc8
	v_cndmask_b32_e32 v129, v130, v129, vcc
	v_lshrrev_b32_e32 v132, 2, v129
	v_lshlrev_b32_e32 v130, 7, v129
	v_xor_b32_e32 v132, v132, v168
	v_and_b32_e32 v130, 0xc00, v130
	v_lshlrev_b32_e32 v131, 5, v129
	v_lshlrev_b32_e32 v132, 3, v132
	v_and_b32_e32 v132, 24, v132
	v_and_or_b32 v130, v131, s79, v130
	v_lshlrev_b32_e32 v129, 8, v129
	v_or3_b32 v132, v130, v132, s64
	v_and_b32_e32 v176, 0x3fc000, v129
	v_pk_fma_f32 v[126:127], v[126:127], v[128:129], v[54:55] op_sel_hi:[1,0,1]
	v_pk_fma_f32 v[124:125], v[124:125], v[128:129], v[52:53] op_sel_hi:[1,0,1]
	v_pk_fma_f32 v[120:121], v[120:121], v[128:129], v[48:49] op_sel_hi:[1,0,1]
	v_pk_fma_f32 v[130:131], v[122:123], v[128:129], v[50:51] op_sel_hi:[1,0,1]
	v_cvt_pk_bf16_f32 v122, v124, v125
	v_cvt_pk_bf16_f32 v123, v126, v127
	v_cvt_pk_bf16_f32 v124, v120, v121
	v_lshl_add_u64 v[126:127], s[14:15], 0, v[176:177]
	v_lshlrev_b32_e32 v120, 1, v132
	v_mov_b32_e32 v121, v177
	v_lshl_add_u64 v[126:127], v[126:127], 0, v[120:121]
	v_pk_fma_f32 v[116:117], v[116:117], v[128:129], v[36:37] op_sel_hi:[1,0,1]
	v_cvt_pk_bf16_f32 v125, v130, v131
	flat_store_dwordx4 v[126:127], v[122:125]
	v_pk_fma_f32 v[118:119], v[118:119], v[128:129], v[38:39] op_sel_hi:[1,0,1]
	s_nop 0
	v_pk_fma_f32 v[122:123], v[114:115], v[128:129], v[34:35] op_sel_hi:[1,0,1]
	v_pk_fma_f32 v[114:115], v[112:113], v[128:129], v[32:33] op_sel_hi:[1,0,1]
	v_cvt_pk_bf16_f32 v112, v116, v117
	v_lshl_add_u64 v[116:117], s[30:31], 0, v[176:177]
	v_lshl_add_u64 v[116:117], v[116:117], 0, v[120:121]
	v_cvt_pk_bf16_f32 v113, v118, v119
	v_cvt_pk_bf16_f32 v114, v114, v115
	v_cvt_pk_bf16_f32 v115, v122, v123
	flat_store_dwordx4 v[116:117], v[112:115]
	s_nop 1
	s_nop 0
	v_bitop3_b32 v114, v158, s81, 32 bitop3:0xc8
	v_add_u32_e32 v114, 0x100, v114
	v_fmamk_f32 v112, v214, 0x3a800000, v224
	v_cmp_gt_f32_e64 s[0:1], s33, v112
	v_mul_f32_e32 v113, 0x4b800000, v112
	s_nop 0
	v_cndmask_b32_e64 v112, v112, v113, s[0:1]
	v_rsq_f32_e32 v112, v112
	s_nop 0
	v_mul_f32_e32 v113, 0x45800000, v112
	v_cndmask_b32_e64 v112, v112, v113, s[0:1]
; __device__ __forceinline__ unsigned pkbf(float lo, float hi) { return pg8::cvt_pk_bf16(lo, hi); }
;     __device__ __forceinline__ void operator()(const f32x4 (&acc)[2][2][4][2], const Unit& u, int wr, int wc, int fr, int fq) const {
;     ...
;         } else if (pn < 6) {
; #pragma unroll
;             for (int ai = 0; ai < 2; ++ai)
; #pragma unroll
;                 for (int m = 0; m < 4; ++m) {
;                     const int row = pm * 256 + ai * 128 + wr * 64 + m * 16 + fr;
;                     const float rinv = rsqrtf(rowsq[row] * (1.f / DM) + EPSN);
;                     int b, kidx;
;                     if (isctx) { const int rc = row - MLAT; b = rc >> 8; kidx = rc & 255; } else { b = row >> 13; kidx = CTXL + (row & (SEQ - 1)); }
; #pragma unroll
;                     for (int bj = 0; bj < 2; ++bj) {
;                         const f32x4 y0 = acc[ai][bj][m][0] * rinv + bv[bj][0], y1 = acc[ai][bj][m][1] * rinv + bv[bj][1];
;                         u32x4 w; w.x = pkbf(y0[0], y0[1]); w.y = pkbf(y0[2], y0[3]); w.z = pkbf(y1[0], y1[1]); w.w = pkbf(y1[2], y1[3]);
;                         const int head = 2 * (pn - 4) + bj;
;                         const size_t off = (size_t)(b * 4 + head) * (LK * 128) + (size_t)(kidx >> 6) * 8192 + (size_t)(voff(kidx & 63, 4 * wc + fq) >> 1);
;                         *(u32x4*)(Vb + off) = w;
;                     }
;                 }
	v_bitop3_b32 v113, v158, s80, 32 bitop3:0xc8
	v_cndmask_b32_e32 v113, v114, v113, vcc
	v_lshrrev_b32_e32 v116, 2, v113
	v_lshlrev_b32_e32 v114, 7, v113
	v_xor_b32_e32 v116, v116, v168
	v_and_b32_e32 v114, 0x1400, v114
	v_lshlrev_b32_e32 v115, 5, v113
	v_lshlrev_b32_e32 v116, 3, v116
	v_and_b32_e32 v116, 24, v116
	v_and_or_b32 v114, v115, s79, v114
	v_lshlrev_b32_e32 v113, 8, v113
	v_or3_b32 v116, v114, v116, s64
	v_and_b32_e32 v176, 0x3fc000, v113
	v_pk_fma_f32 v[110:111], v[110:111], v[112:113], v[54:55] op_sel_hi:[1,0,1]
	v_pk_fma_f32 v[108:109], v[108:109], v[112:113], v[52:53] op_sel_hi:[1,0,1]
	v_pk_fma_f32 v[104:105], v[104:105], v[112:113], v[48:49] op_sel_hi:[1,0,1]
	v_pk_fma_f32 v[114:115], v[106:107], v[112:113], v[50:51] op_sel_hi:[1,0,1]
	v_cvt_pk_bf16_f32 v106, v108, v109
	v_cvt_pk_bf16_f32 v107, v110, v111
	v_cvt_pk_bf16_f32 v108, v104, v105
	v_lshl_add_u64 v[110:111], s[14:15], 0, v[176:177]
	v_lshlrev_b32_e32 v104, 1, v116
	v_mov_b32_e32 v105, v177
	v_lshl_add_u64 v[110:111], v[110:111], 0, v[104:105]
	v_pk_fma_f32 v[100:101], v[100:101], v[112:113], v[36:37] op_sel_hi:[1,0,1]
	v_cvt_pk_bf16_f32 v109, v114, v115
	flat_store_dwordx4 v[110:111], v[106:109]
	v_pk_fma_f32 v[102:103], v[102:103], v[112:113], v[38:39] op_sel_hi:[1,0,1]
	s_nop 0
	v_pk_fma_f32 v[106:107], v[98:99], v[112:113], v[34:35] op_sel_hi:[1,0,1]
	v_pk_fma_f32 v[98:99], v[96:97], v[112:113], v[32:33] op_sel_hi:[1,0,1]
	v_cvt_pk_bf16_f32 v96, v100, v101
	v_lshl_add_u64 v[100:101], s[30:31], 0, v[176:177]
	v_lshl_add_u64 v[100:101], v[100:101], 0, v[104:105]
	v_cvt_pk_bf16_f32 v97, v102, v103
	v_cvt_pk_bf16_f32 v98, v98, v99
	v_cvt_pk_bf16_f32 v99, v106, v107
	flat_store_dwordx4 v[100:101], v[96:99]
	s_nop 1
	s_nop 0
	v_bitop3_b32 v98, v158, s68, 48 bitop3:0xc8
	v_add_u32_e32 v98, 0x100, v98
	v_fmamk_f32 v96, v215, 0x3a800000, v224
	v_cmp_gt_f32_e64 s[0:1], s33, v96
	v_mul_f32_e32 v97, 0x4b800000, v96
	s_nop 0
	v_cndmask_b32_e64 v96, v96, v97, s[0:1]
	v_rsq_f32_e32 v96, v96
	s_nop 0
	v_mul_f32_e32 v97, 0x45800000, v96
	v_cndmask_b32_e64 v96, v96, v97, s[0:1]
	v_bitop3_b32 v97, v158, s48, 48 bitop3:0xc8
	v_cndmask_b32_e32 v97, v98, v97, vcc
	v_lshrrev_b32_e32 v100, 2, v97
	v_lshlrev_b32_e32 v98, 7, v97
	v_xor_b32_e32 v100, v100, v168
	v_and_b32_e32 v98, 0x1c00, v98
	v_lshlrev_b32_e32 v99, 5, v97
	v_lshlrev_b32_e32 v100, 3, v100
	v_and_b32_e32 v100, 24, v100
	v_and_or_b32 v98, v99, s79, v98
	v_lshlrev_b32_e32 v97, 8, v97
	v_or3_b32 v100, v98, v100, s64
	v_and_b32_e32 v176, 0x3fc000, v97
	v_pk_fma_f32 v[94:95], v[94:95], v[96:97], v[54:55] op_sel_hi:[1,0,1]
	v_pk_fma_f32 v[92:93], v[92:93], v[96:97], v[52:53] op_sel_hi:[1,0,1]
	v_pk_fma_f32 v[98:99], v[90:91], v[96:97], v[50:51] op_sel_hi:[1,0,1]
	v_pk_fma_f32 v[90:91], v[88:89], v[96:97], v[48:49] op_sel_hi:[1,0,1]
	v_cvt_pk_bf16_f32 v88, v92, v93
	v_cvt_pk_bf16_f32 v89, v94, v95
	v_lshl_add_u64 v[92:93], s[14:15], 0, v[176:177]
	v_lshlrev_b32_e32 v94, 1, v100
	v_mov_b32_e32 v95, v177
	v_lshl_add_u64 v[92:93], v[92:93], 0, v[94:95]
	v_pk_fma_f32 v[84:85], v[84:85], v[96:97], v[36:37] op_sel_hi:[1,0,1]
	v_cvt_pk_bf16_f32 v90, v90, v91
	v_cvt_pk_bf16_f32 v91, v98, v99
	flat_store_dwordx4 v[92:93], v[88:91]
	v_pk_fma_f32 v[86:87], v[86:87], v[96:97], v[38:39] op_sel_hi:[1,0,1]
	s_nop 0
	v_pk_fma_f32 v[88:89], v[82:83], v[96:97], v[34:35] op_sel_hi:[1,0,1]
	v_pk_fma_f32 v[82:83], v[80:81], v[96:97], v[32:33] op_sel_hi:[1,0,1]
	v_cvt_pk_bf16_f32 v80, v84, v85
	v_lshl_add_u64 v[84:85], s[30:31], 0, v[176:177]
	v_lshl_add_u64 v[84:85], v[84:85], 0, v[94:95]
	v_cvt_pk_bf16_f32 v81, v86, v87
	v_cvt_pk_bf16_f32 v82, v82, v83
	v_cvt_pk_bf16_f32 v83, v88, v89
	flat_store_dwordx4 v[84:85], v[80:83]
	v_bitop3_b32 v85, s23, v228, v169 bitop3:0xc8
	v_add_u32_e32 v85, 0x100, v85
	v_or_b32_e32 v80, s23, v169
	v_ashrrev_i32_e32 v81, 31, v80
	v_lshl_add_u64 v[82:83], v[80:81], 2, s[12:13]
	flat_load_dword v81, v[82:83]
	flat_load_dword v214, v[82:83] offset:64
	flat_load_dword v215, v[82:83] offset:128
	flat_load_dword v216, v[82:83] offset:192
	s_waitcnt vmcnt(0) lgkmcnt(0)
	v_fmamk_f32 v81, v81, 0x3a800000, v224
	v_cmp_gt_f32_e64 s[0:1], s33, v81
	v_mul_f32_e32 v84, 0x4b800000, v81
	s_nop 0
	v_cndmask_b32_e64 v81, v81, v84, s[0:1]
	v_rsq_f32_e32 v81, v81
	s_nop 0
	v_mul_f32_e32 v84, 0x45800000, v81
	v_cndmask_b32_e64 v84, v81, v84, s[0:1]
	v_bitop3_b32 v81, s23, v227, v169 bitop3:0xc8
	v_cndmask_b32_e32 v81, v85, v81, vcc
	s_lshl_b32 s0, s54, 2
	v_lshrrev_b32_e32 v87, 2, v81
	s_add_i32 s0, s0, s21
	v_lshlrev_b32_e32 v85, 7, v81
	v_xor_b32_e32 v87, v87, v168
	v_and_b32_e32 v85, 0x400, v85
	v_lshlrev_b32_e32 v86, 5, v81
	v_lshlrev_b32_e32 v87, 3, v87
	s_mul_i32 s14, s0, 0x210000
	v_and_b32_e32 v87, 24, v87
	v_and_or_b32 v85, v86, s79, v85
	s_mul_hi_i32 s1, s0, 0x210000
	s_add_u32 s14, s45, s14
	v_or3_b32 v85, v85, v87, s64
	v_lshlrev_b32_e32 v81, 8, v81
	s_addc_u32 s15, s46, s1
	s_or_b32 s0, s0, 1
	v_and_b32_e32 v176, 0x3fc000, v81
	v_pk_fma_f32 v[78:79], v[78:79], v[84:85], v[54:55] op_sel_hi:[1,0,1]
	v_pk_fma_f32 v[76:77], v[76:77], v[84:85], v[52:53] op_sel_hi:[1,0,1]
	v_pk_fma_f32 v[72:73], v[72:73], v[84:85], v[48:49] op_sel_hi:[1,0,1]
	s_mul_hi_i32 s1, s0, 0x210000
	s_mul_i32 s0, s0, 0x210000
	v_pk_fma_f32 v[86:87], v[74:75], v[84:85], v[50:51] op_sel_hi:[1,0,1]
	v_cvt_pk_bf16_f32 v74, v76, v77
	v_cvt_pk_bf16_f32 v75, v78, v79
	v_cvt_pk_bf16_f32 v76, v72, v73
	v_lshl_add_u64 v[78:79], s[14:15], 0, v[176:177]
	v_lshlrev_b32_e32 v72, 1, v85
	v_mov_b32_e32 v73, v177
	s_add_u32 s30, s45, s0
	v_lshl_add_u64 v[78:79], v[78:79], 0, v[72:73]
	v_pk_fma_f32 v[68:69], v[68:69], v[84:85], v[36:37] op_sel_hi:[1,0,1]
	s_addc_u32 s31, s46, s1
; __device__ __forceinline__ unsigned pkbf(float lo, float hi) { return pg8::cvt_pk_bf16(lo, hi); }
;     __device__ __forceinline__ void operator()(const f32x4 (&acc)[2][2][4][2], const Unit& u, int wr, int wc, int fr, int fq) const {
;     ...
;         } else if (pn < 6) {
; #pragma unroll
;             for (int ai = 0; ai < 2; ++ai)
; #pragma unroll
;                 for (int m = 0; m < 4; ++m) {
;                     const int row = pm * 256 + ai * 128 + wr * 64 + m * 16 + fr;
;                     const float rinv = rsqrtf(rowsq[row] * (1.f / DM) + EPSN);
;                     int b, kidx;
;                     if (isctx) { const int rc = row - MLAT; b = rc >> 8; kidx = rc & 255; } else { b = row >> 13; kidx = CTXL + (row & (SEQ - 1)); }
; #pragma unroll
;                     for (int bj = 0; bj < 2; ++bj) {
;                         const f32x4 y0 = acc[ai][bj][m][0] * rinv + bv[bj][0], y1 = acc[ai][bj][m][1] * rinv + bv[bj][1];
;                         u32x4 w; w.x = pkbf(y0[0], y0[1]); w.y = pkbf(y0[2], y0[3]); w.z = pkbf(y1[0], y1[1]); w.w = pkbf(y1[2], y1[3]);
;                         const int head = 2 * (pn - 4) + bj;
;                         const size_t off = (size_t)(b * 4 + head) * (LK * 128) + (size_t)(kidx >> 6) * 8192 + (size_t)(voff(kidx & 63, 4 * wc + fq) >> 1);
;                         *(u32x4*)(Vb + off) = w;
;                     }
;                 }
	v_cvt_pk_bf16_f32 v77, v86, v87
	flat_store_dwordx4 v[78:79], v[74:77]
	v_pk_fma_f32 v[70:71], v[70:71], v[84:85], v[38:39] op_sel_hi:[1,0,1]
	s_nop 0
	v_pk_fma_f32 v[74:75], v[66:67], v[84:85], v[34:35] op_sel_hi:[1,0,1]
	v_pk_fma_f32 v[66:67], v[64:65], v[84:85], v[32:33] op_sel_hi:[1,0,1]
	v_cvt_pk_bf16_f32 v64, v68, v69
	v_lshl_add_u64 v[68:69], s[30:31], 0, v[176:177]
	v_lshl_add_u64 v[68:69], v[68:69], 0, v[72:73]
	v_cvt_pk_bf16_f32 v65, v70, v71
	v_cvt_pk_bf16_f32 v66, v66, v67
	v_cvt_pk_bf16_f32 v67, v74, v75
	flat_store_dwordx4 v[68:69], v[64:67]
	s_nop 1
	s_nop 0
	v_bitop3_b32 v66, v80, s84, 16 bitop3:0xc8
	v_add_u32_e32 v66, 0x100, v66
	v_fmamk_f32 v64, v214, 0x3a800000, v224
	v_cmp_gt_f32_e64 s[0:1], s33, v64
	v_mul_f32_e32 v65, 0x4b800000, v64
	s_nop 0
	v_cndmask_b32_e64 v64, v64, v65, s[0:1]
	v_rsq_f32_e32 v64, v64
	s_nop 0
	v_mul_f32_e32 v65, 0x45800000, v64
	v_cndmask_b32_e64 v64, v64, v65, s[0:1]
	v_bitop3_b32 v65, v80, s95, 16 bitop3:0xc8
	v_cndmask_b32_e32 v65, v66, v65, vcc
	v_lshrrev_b32_e32 v68, 2, v65
	v_lshlrev_b32_e32 v66, 7, v65
	v_xor_b32_e32 v68, v68, v168
	v_and_b32_e32 v66, 0xc00, v66
	v_lshlrev_b32_e32 v67, 5, v65
	v_lshlrev_b32_e32 v68, 3, v68
	v_and_b32_e32 v68, 24, v68
	v_and_or_b32 v66, v67, s79, v66
	v_lshlrev_b32_e32 v65, 8, v65
	v_or3_b32 v68, v66, v68, s64
	v_and_b32_e32 v176, 0x3fc000, v65
	v_pk_fma_f32 v[62:63], v[62:63], v[64:65], v[54:55] op_sel_hi:[1,0,1]
	v_pk_fma_f32 v[60:61], v[60:61], v[64:65], v[52:53] op_sel_hi:[1,0,1]
	v_pk_fma_f32 v[56:57], v[56:57], v[64:65], v[48:49] op_sel_hi:[1,0,1]
	v_pk_fma_f32 v[66:67], v[58:59], v[64:65], v[50:51] op_sel_hi:[1,0,1]
	v_cvt_pk_bf16_f32 v58, v60, v61
	v_cvt_pk_bf16_f32 v59, v62, v63
	v_cvt_pk_bf16_f32 v60, v56, v57
	v_lshl_add_u64 v[62:63], s[14:15], 0, v[176:177]
	v_lshlrev_b32_e32 v56, 1, v68
	v_mov_b32_e32 v57, v177
	v_lshl_add_u64 v[62:63], v[62:63], 0, v[56:57]
	v_pk_fma_f32 v[44:45], v[44:45], v[64:65], v[36:37] op_sel_hi:[1,0,1]
	v_cvt_pk_bf16_f32 v61, v66, v67
	flat_store_dwordx4 v[62:63], v[58:61]
	v_pk_fma_f32 v[46:47], v[46:47], v[64:65], v[38:39] op_sel_hi:[1,0,1]
	s_nop 0
	v_pk_fma_f32 v[58:59], v[42:43], v[64:65], v[34:35] op_sel_hi:[1,0,1]
	v_pk_fma_f32 v[42:43], v[40:41], v[64:65], v[32:33] op_sel_hi:[1,0,1]
	v_cvt_pk_bf16_f32 v40, v44, v45
	v_lshl_add_u64 v[44:45], s[30:31], 0, v[176:177]
	v_lshl_add_u64 v[44:45], v[44:45], 0, v[56:57]
	v_cvt_pk_bf16_f32 v41, v46, v47
	v_cvt_pk_bf16_f32 v42, v42, v43
	v_cvt_pk_bf16_f32 v43, v58, v59
	flat_store_dwordx4 v[44:45], v[40:43]
	s_nop 1
	s_nop 0
	v_bitop3_b32 v42, v80, s81, 32 bitop3:0xc8
	v_add_u32_e32 v42, 0x100, v42
	v_fmamk_f32 v40, v215, 0x3a800000, v224
	v_cmp_gt_f32_e64 s[0:1], s33, v40
	v_mul_f32_e32 v41, 0x4b800000, v40
	s_nop 0
	v_cndmask_b32_e64 v40, v40, v41, s[0:1]
	v_rsq_f32_e32 v40, v40
	s_nop 0
	v_mul_f32_e32 v41, 0x45800000, v40
	v_cndmask_b32_e64 v40, v40, v41, s[0:1]
	v_bitop3_b32 v41, v80, s80, 32 bitop3:0xc8
	v_cndmask_b32_e32 v41, v42, v41, vcc
	v_lshrrev_b32_e32 v44, 2, v41
	v_lshlrev_b32_e32 v42, 7, v41
	v_xor_b32_e32 v44, v44, v168
	v_and_b32_e32 v42, 0x1400, v42
	v_lshlrev_b32_e32 v43, 5, v41
	v_lshlrev_b32_e32 v44, 3, v44
	v_and_b32_e32 v44, 24, v44
	v_and_or_b32 v42, v43, s79, v42
	v_lshlrev_b32_e32 v41, 8, v41
	v_or3_b32 v44, v42, v44, s64
	v_and_b32_e32 v176, 0x3fc000, v41
	v_pk_fma_f32 v[30:31], v[30:31], v[40:41], v[54:55] op_sel_hi:[1,0,1]
	v_pk_fma_f32 v[28:29], v[28:29], v[40:41], v[52:53] op_sel_hi:[1,0,1]
	v_pk_fma_f32 v[24:25], v[24:25], v[40:41], v[48:49] op_sel_hi:[1,0,1]
	v_pk_fma_f32 v[42:43], v[26:27], v[40:41], v[50:51] op_sel_hi:[1,0,1]
	v_cvt_pk_bf16_f32 v26, v28, v29
	v_cvt_pk_bf16_f32 v27, v30, v31
	v_cvt_pk_bf16_f32 v28, v24, v25
	v_lshl_add_u64 v[30:31], s[14:15], 0, v[176:177]
	v_lshlrev_b32_e32 v24, 1, v44
	v_mov_b32_e32 v25, v177
	v_lshl_add_u64 v[30:31], v[30:31], 0, v[24:25]
	v_pk_fma_f32 v[20:21], v[20:21], v[40:41], v[36:37] op_sel_hi:[1,0,1]
	v_cvt_pk_bf16_f32 v29, v42, v43
	flat_store_dwordx4 v[30:31], v[26:29]
	v_pk_fma_f32 v[22:23], v[22:23], v[40:41], v[38:39] op_sel_hi:[1,0,1]
	s_nop 0
	v_pk_fma_f32 v[26:27], v[18:19], v[40:41], v[34:35] op_sel_hi:[1,0,1]
	v_pk_fma_f32 v[18:19], v[16:17], v[40:41], v[32:33] op_sel_hi:[1,0,1]
	v_cvt_pk_bf16_f32 v16, v20, v21
	v_lshl_add_u64 v[20:21], s[30:31], 0, v[176:177]
	v_lshl_add_u64 v[20:21], v[20:21], 0, v[24:25]
	v_cvt_pk_bf16_f32 v17, v22, v23
	v_cvt_pk_bf16_f32 v18, v18, v19
	v_cvt_pk_bf16_f32 v19, v26, v27
	flat_store_dwordx4 v[20:21], v[16:19]
	s_nop 1
	s_nop 0
	v_bitop3_b32 v18, v80, s68, 48 bitop3:0xc8
	v_add_u32_e32 v18, 0x100, v18
	v_fmamk_f32 v16, v216, 0x3a800000, v224
	v_cmp_gt_f32_e64 s[0:1], s33, v16
	v_mul_f32_e32 v17, 0x4b800000, v16
	s_nop 0
	v_cndmask_b32_e64 v16, v16, v17, s[0:1]
	v_rsq_f32_e32 v16, v16
	s_nop 0
	v_mul_f32_e32 v17, 0x45800000, v16
	v_cndmask_b32_e64 v16, v16, v17, s[0:1]
	v_bitop3_b32 v17, v80, s48, 48 bitop3:0xc8
	v_cndmask_b32_e32 v17, v18, v17, vcc
	v_lshrrev_b32_e32 v20, 2, v17
	v_lshlrev_b32_e32 v18, 7, v17
	v_xor_b32_e32 v20, v20, v168
	v_and_b32_e32 v18, 0x1c00, v18
	v_lshlrev_b32_e32 v19, 5, v17
	v_lshlrev_b32_e32 v20, 3, v20
	v_and_b32_e32 v20, 24, v20
	v_and_or_b32 v18, v19, s79, v18
	v_lshlrev_b32_e32 v17, 8, v17
	v_or3_b32 v20, v18, v20, s64
	v_and_b32_e32 v176, 0x3fc000, v17
	v_pk_fma_f32 v[14:15], v[14:15], v[16:17], v[54:55] op_sel_hi:[1,0,1]
	v_pk_fma_f32 v[12:13], v[12:13], v[16:17], v[52:53] op_sel_hi:[1,0,1]
	v_pk_fma_f32 v[8:9], v[8:9], v[16:17], v[48:49] op_sel_hi:[1,0,1]
	v_pk_fma_f32 v[18:19], v[10:11], v[16:17], v[50:51] op_sel_hi:[1,0,1]
	v_cvt_pk_bf16_f32 v10, v12, v13
	v_cvt_pk_bf16_f32 v11, v14, v15
	v_cvt_pk_bf16_f32 v12, v8, v9
	v_lshl_add_u64 v[14:15], s[14:15], 0, v[176:177]
	v_lshlrev_b32_e32 v8, 1, v20
	v_mov_b32_e32 v9, v177
	v_lshl_add_u64 v[14:15], v[14:15], 0, v[8:9]
	v_pk_fma_f32 v[4:5], v[4:5], v[16:17], v[36:37] op_sel_hi:[1,0,1]
	v_cvt_pk_bf16_f32 v13, v18, v19
	flat_store_dwordx4 v[14:15], v[10:13]
	v_pk_fma_f32 v[6:7], v[6:7], v[16:17], v[38:39] op_sel_hi:[1,0,1]
	s_nop 0
	v_pk_fma_f32 v[10:11], v[2:3], v[16:17], v[34:35] op_sel_hi:[1,0,1]
	v_pk_fma_f32 v[2:3], v[0:1], v[16:17], v[32:33] op_sel_hi:[1,0,1]
	v_cvt_pk_bf16_f32 v0, v4, v5
	v_lshl_add_u64 v[4:5], s[30:31], 0, v[176:177]
	v_lshl_add_u64 v[4:5], v[4:5], 0, v[8:9]
	v_cvt_pk_bf16_f32 v1, v6, v7
	v_cvt_pk_bf16_f32 v2, v2, v3
	v_cvt_pk_bf16_f32 v3, v10, v11
	flat_store_dwordx4 v[4:5], v[0:3]
	s_andn2_b64 vcc, exec, s[26:27]
	s_mov_b64 s[0:1], -1
	s_cbranch_vccnz .LBB0_312
